# RG-LRU 32-lane segmented scan: ds_bpermute shifts replaced by row-local DPP row_shr steps + row_bcast:15 final step
# speedup vs baseline: 1.0122x; 1.0041x over previous
.Llru_tail:
	s_movk_i32 s0, 0x110
	v_ashrrev_i32_e32 v161, 6, v160
	v_and_b32_e32 v162, 31, v160
	v_mul_lo_u32 v33, v36, s0
	v_lshlrev_b32_e32 v34, 2, v37
	v_add3_u32 v33, s89, v33, v34
	v_lshl_or_b32 v163, v161, 5, v162
	s_waitcnt vmcnt(6)
	ds_write_b128 v33, v[4:7]
	ds_write_b128 v33, v[0:3] offset:16
	s_waitcnt vmcnt(4)
	ds_write_b128 v33, v[12:15] offset:32
	ds_write_b128 v33, v[8:11] offset:48
	s_waitcnt vmcnt(2)
	ds_write_b128 v33, v[20:23] offset:64
	ds_write_b128 v33, v[16:19] offset:80
	s_waitcnt vmcnt(0)
	ds_write_b128 v33, v[28:31] offset:96
	ds_write_b128 v33, v[24:27] offset:112
	v_mul_lo_u32 v0, v163, s0
	v_and_b32_e32 v1, 32, v160
	v_add3_u32 v64, s89, v0, v1
	s_waitcnt lgkmcnt(0)
	s_barrier
	ds_read_b128 v[0:3], v64
	ds_read_b128 v[4:7], v64 offset:16
	v_bfe_u32 v32, v160, 5, 1
	v_lshlrev_b32_e32 v168, 4, v32
	v_lshlrev_b32_e32 v100, 7, v162
	s_waitcnt lgkmcnt(1)
	v_cvt_pk_bf16_f32 v56, v0, v1
	v_cvt_pk_bf16_f32 v57, v2, v3
	s_waitcnt lgkmcnt(0)
	v_cvt_pk_bf16_f32 v58, v4, v5
	v_cvt_pk_bf16_f32 v59, v6, v7
	ds_read_b128 v[0:3], v64 offset:64
	ds_read_b128 v[4:7], v64 offset:80
	v_mov_b32_e32 v101, v169
	v_lshlrev_b32_e32 v164, 2, v32
	v_sub_u32_e32 v124, v64, v168
	s_waitcnt lgkmcnt(1)
	v_cvt_pk_bf16_f32 v52, v0, v1
	v_cvt_pk_bf16_f32 v53, v2, v3
	s_waitcnt lgkmcnt(0)
	v_cvt_pk_bf16_f32 v54, v4, v5
	v_cvt_pk_bf16_f32 v55, v6, v7
	ds_read_b128 v[0:3], v64 offset:128
	ds_read_b128 v[4:7], v64 offset:144
	s_waitcnt lgkmcnt(1)
	v_cvt_pk_bf16_f32 v48, v0, v1
	v_cvt_pk_bf16_f32 v49, v2, v3
	s_waitcnt lgkmcnt(0)
	v_cvt_pk_bf16_f32 v50, v4, v5
	v_cvt_pk_bf16_f32 v51, v6, v7
	ds_read_b128 v[0:3], v64 offset:192
	ds_read_b128 v[4:7], v64 offset:208
	s_load_dwordx2 s[6:7], s[54:55], 0x98
	s_load_dwordx4 s[0:3], s[54:55], 0xa8
	s_waitcnt lgkmcnt(0)
	v_cvt_pk_bf16_f32 v44, v0, v1
	s_add_u32 s5, s6, s60
	s_addc_u32 s6, s7, s61
	s_lshl_b32 s75, s74, 2
	s_add_u32 s10, s5, s75
	s_addc_u32 s11, s6, 0
	s_add_u32 s0, s0, s60
	s_addc_u32 s1, s1, s61
	s_add_u32 s12, s0, s75
	s_addc_u32 s13, s1, 0
	s_add_u32 s0, s2, s60
	s_addc_u32 s1, s3, s61
	s_add_u32 s8, s0, s75
	s_addc_u32 s9, s1, 0
	s_lshl_b32 s2, s4, 13
	s_add_u32 s0, s36, s2
	s_addc_u32 s1, s37, 0
	v_lshl_add_u64 v[96:97], s[0:1], 0, v[168:169]
	s_add_u32 s0, s38, s2
	s_addc_u32 s1, s39, 0
	v_lshl_add_u64 v[98:99], s[0:1], 0, v[168:169]
	v_lshl_add_u64 v[40:41], v[96:97], 0, v[100:101]
	v_cvt_pk_bf16_f32 v45, v2, v3
	v_cvt_pk_bf16_f32 v46, v4, v5
	v_cvt_pk_bf16_f32 v47, v6, v7
	v_lshl_add_u64 v[42:43], v[98:99], 0, v[100:101]
	global_load_dwordx4 v[0:3], v[40:41], off
	global_load_dwordx4 v[4:7], v[42:43], off
	global_load_dwordx4 v[32:35], v[40:41], off offset:32
	global_load_dwordx4 v[36:39], v[42:43], off offset:32
	s_mov_b32 s0, 0x3f317217
	s_mov_b32 s1, 0x7f800000
	s_mov_b32 s3, 0x3cf5c28f
	s_mov_b32 s2, 0xc1700000
	s_mov_b32 s4, 0xbdcccccd
	s_waitcnt vmcnt(3)
	v_mfma_f32_32x32x16_bf16 v[16:31], v[0:3], v[56:59], 0
	s_waitcnt vmcnt(2)
	v_mfma_f32_32x32x16_bf16 v[0:15], v[4:7], v[56:59], 0
	s_waitcnt vmcnt(1)
	v_mfma_f32_32x32x16_bf16 v[16:31], v[32:35], v[52:55], v[16:31]
	s_waitcnt vmcnt(0)
	v_mfma_f32_32x32x16_bf16 v[0:15], v[36:39], v[52:55], v[0:15]
	global_load_dwordx4 v[32:35], v[40:41], off offset:64
	global_load_dwordx4 v[36:39], v[42:43], off offset:64
	s_waitcnt vmcnt(1)
	v_mfma_f32_32x32x16_bf16 v[16:31], v[32:35], v[48:51], v[16:31]
	s_waitcnt vmcnt(0)
	v_mfma_f32_32x32x16_bf16 v[0:15], v[36:39], v[48:51], v[0:15]
	global_load_dwordx4 v[32:35], v[40:41], off offset:96
	global_load_dwordx4 v[36:39], v[42:43], off offset:96
	s_waitcnt vmcnt(1)
	v_mfma_f32_32x32x16_bf16 v[16:31], v[32:35], v[44:47], v[16:31]
	s_waitcnt vmcnt(0)
	v_mfma_f32_32x32x16_bf16 v[0:15], v[36:39], v[44:47], v[0:15]
	global_load_dwordx4 v[40:43], v168, s[10:11]
	global_load_dwordx4 v[36:39], v168, s[12:13]
	global_load_dwordx4 v[60:63], v168, s[8:9]
	ds_read_b128 v[64:67], v124
	ds_read_b128 v[32:35], v124 offset:32
	s_waitcnt vmcnt(2)
	s_nop 3
	v_add_f32_e32 v16, v16, v40
	s_waitcnt vmcnt(1)
	v_add_f32_e32 v0, v0, v36
	s_waitcnt vmcnt(0)
	v_mul_f32_e32 v36, 0xbfb8aa3b, v60
	v_exp_f32_e32 v36, v36
	v_mul_f32_e32 v16, 0xbfb8aa3b, v16
	v_exp_f32_e32 v16, v16
	v_mul_f32_e32 v0, 0xbfb8aa3b, v0
	v_add_f32_e32 v40, 1.0, v36
	v_cmp_gt_f32_e32 vcc, s28, v40
	v_add_f32_e32 v16, 1.0, v16
	v_rcp_f32_e32 v16, v16
	v_cndmask_b32_e64 v68, 0, 32, vcc
	v_ldexp_f32 v40, v40, v68
	v_log_f32_e32 v40, v40
	v_mul_f32_e32 v16, 0xc1000000, v16
	v_exp_f32_e32 v0, v0
	v_add_f32_e32 v1, v1, v37
	v_mul_f32_e32 v68, 0x3f317217, v40
	v_fma_f32 v68, v40, s0, -v68
	v_fmac_f32_e32 v68, 0x3377d1cf, v40
	v_fmac_f32_e32 v68, 0x3f317217, v40
	v_cmp_lt_f32_e64 s[6:7], |v40|, s1
	v_add_f32_e32 v0, 1.0, v0
	v_rcp_f32_e32 v0, v0
	v_cndmask_b32_e64 v40, v40, v68, s[6:7]
	v_cndmask_b32_e32 v68, 0, v201, vcc
	v_sub_f32_e32 v40, v40, v68
	v_fmamk_f32 v68, v36, 0xbe800000, v188
	v_fma_f32 v68, -v36, v68, 0.5
	v_fma_f32 v68, -v36, v68, 1.0
	v_mul_f32_e32 v68, v36, v68
	v_cmp_gt_f32_e64 s[6:7], s3, v36
	v_cmp_gt_f32_e32 vcc, s2, v60
	s_waitcnt lgkmcnt(1)
	v_mul_f32_e32 v0, v64, v0
	v_cndmask_b32_e64 v36, v40, v68, s[6:7]
	v_cndmask_b32_e64 v36, v36, -v60, vcc
	v_mul_f32_e32 v16, v16, v36
	v_mul_f32_e32 v36, 0x3fb8aa3b, v16
	v_add_f32_e32 v16, v16, v16
	v_mul_f32_e32 v40, 0x3fb8aa3b, v16
	v_exp_f32_e32 v136, v36
	v_fmamk_f32 v36, v16, 0x3c088889, v189
	v_exp_f32_e32 v40, v40
	v_fmaak_f32 v36, v16, v36, 0x3e2aaaab
	v_fma_f32 v36, v16, v36, 0.5
	v_fma_f32 v36, v16, v36, 1.0
	v_mul_f32_e64 v36, v36, -v16
	v_sub_f32_e32 v40, 1.0, v40
	v_cmp_lt_f32_e32 vcc, s4, v16
	v_mul_f32_e32 v1, 0xbfb8aa3b, v1
	v_exp_f32_e32 v1, v1
	v_cndmask_b32_e32 v16, v40, v36, vcc
	v_sqrt_f32_e32 v16, v16
	v_add_f32_e32 v1, 1.0, v1
	v_rcp_f32_e32 v1, v1
	v_mul_f32_e32 v137, v0, v16
	v_mul_f32_e32 v16, 0xbfb8aa3b, v61
	v_exp_f32_e32 v16, v16
	v_add_f32_e32 v0, v17, v41
	v_mul_f32_e32 v0, 0xbfb8aa3b, v0
	v_exp_f32_e32 v0, v0
	v_add_f32_e32 v17, 1.0, v16
	v_cmp_gt_f32_e32 vcc, s28, v17
	v_mul_f32_e32 v1, v65, v1
	v_add_f32_e32 v0, 1.0, v0
	v_cndmask_b32_e64 v36, 0, 32, vcc
	v_ldexp_f32 v17, v17, v36
	v_log_f32_e32 v17, v17
	v_rcp_f32_e32 v0, v0
	v_mul_f32_e32 v36, 0x3f317217, v17
	v_fma_f32 v36, v17, s0, -v36
	v_fmac_f32_e32 v36, 0x3377d1cf, v17
	v_fmac_f32_e32 v36, 0x3f317217, v17
	v_cmp_lt_f32_e64 s[6:7], |v17|, s1
	v_mul_f32_e32 v0, 0xc1000000, v0
	s_nop 0
	v_cndmask_b32_e64 v17, v17, v36, s[6:7]
	v_cndmask_b32_e32 v36, 0, v201, vcc
	v_sub_f32_e32 v17, v17, v36
	v_fmamk_f32 v36, v16, 0xbe800000, v188
	v_fma_f32 v36, -v16, v36, 0.5
	v_fma_f32 v36, -v16, v36, 1.0
	v_mul_f32_e32 v36, v16, v36
	v_cmp_gt_f32_e64 s[6:7], s3, v16
	v_cmp_gt_f32_e32 vcc, s2, v61
	s_nop 0
	v_cndmask_b32_e64 v16, v17, v36, s[6:7]
	v_cndmask_b32_e64 v16, v16, -v61, vcc
	v_mul_f32_e32 v0, v0, v16
	v_mul_f32_e32 v16, 0x3fb8aa3b, v0
	v_add_f32_e32 v0, v0, v0
	v_mul_f32_e32 v17, 0x3fb8aa3b, v0
	v_exp_f32_e32 v138, v16
	v_fmamk_f32 v16, v0, 0x3c088889, v189
	v_exp_f32_e32 v17, v17
	v_fmaak_f32 v16, v0, v16, 0x3e2aaaab
	v_fma_f32 v16, v0, v16, 0.5
	v_fma_f32 v16, v0, v16, 1.0
	v_mul_f32_e64 v16, v16, -v0
	v_sub_f32_e32 v17, 1.0, v17
	v_cmp_lt_f32_e32 vcc, s4, v0
	s_nop 1
	v_cndmask_b32_e32 v0, v17, v16, vcc
	v_sqrt_f32_e32 v0, v0
	s_nop 0
	v_mul_f32_e32 v139, v1, v0
	v_add_f32_e32 v1, v2, v38
	v_mul_f32_e32 v2, 0xbfb8aa3b, v62
	v_exp_f32_e32 v2, v2
	v_add_f32_e32 v0, v18, v42
	v_mul_f32_e32 v0, 0xbfb8aa3b, v0
	v_exp_f32_e32 v0, v0
	v_add_f32_e32 v16, 1.0, v2
	v_cmp_gt_f32_e32 vcc, s28, v16
	v_mul_f32_e32 v1, 0xbfb8aa3b, v1
	v_add_f32_e32 v0, 1.0, v0
	v_cndmask_b32_e64 v17, 0, 32, vcc
	v_ldexp_f32 v16, v16, v17
	v_log_f32_e32 v16, v16
	v_rcp_f32_e32 v0, v0
	v_exp_f32_e32 v1, v1
	v_mul_f32_e32 v17, 0x3f317217, v16
	v_fma_f32 v17, v16, s0, -v17
	v_fmac_f32_e32 v17, 0x3377d1cf, v16
	v_fmac_f32_e32 v17, 0x3f317217, v16
	v_cmp_lt_f32_e64 s[6:7], |v16|, s1
	v_mul_f32_e32 v0, 0xc1000000, v0
	v_add_f32_e32 v1, 1.0, v1
	v_cndmask_b32_e64 v16, v16, v17, s[6:7]
	v_cndmask_b32_e32 v17, 0, v201, vcc
	v_sub_f32_e32 v16, v16, v17
	v_fmamk_f32 v17, v2, 0xbe800000, v188
	v_fma_f32 v17, -v2, v17, 0.5
	v_fma_f32 v17, -v2, v17, 1.0
	v_mul_f32_e32 v17, v2, v17
	v_cmp_gt_f32_e64 s[6:7], s3, v2
	v_cmp_gt_f32_e32 vcc, s2, v62
	v_rcp_f32_e32 v1, v1
	v_cndmask_b32_e64 v2, v16, v17, s[6:7]
	v_cndmask_b32_e64 v2, v2, -v62, vcc
	v_mul_f32_e32 v0, v0, v2
	v_mul_f32_e32 v2, 0x3fb8aa3b, v0
	v_add_f32_e32 v0, v0, v0
	v_mul_f32_e32 v16, 0x3fb8aa3b, v0
	v_exp_f32_e32 v140, v2
	v_fmamk_f32 v2, v0, 0x3c088889, v189
	v_exp_f32_e32 v16, v16
	v_fmaak_f32 v2, v0, v2, 0x3e2aaaab
	v_fma_f32 v2, v0, v2, 0.5
	v_fma_f32 v2, v0, v2, 1.0
	v_mul_f32_e64 v2, v2, -v0
	v_sub_f32_e32 v16, 1.0, v16
	v_cmp_lt_f32_e32 vcc, s4, v0
	v_mul_f32_e32 v1, v66, v1
	s_nop 0
	v_cndmask_b32_e32 v0, v16, v2, vcc
	v_mul_f32_e32 v2, 0xbfb8aa3b, v63
	v_sqrt_f32_e32 v0, v0
	v_exp_f32_e32 v2, v2
	v_mul_f32_e32 v141, v1, v0
	v_add_f32_e32 v1, v3, v39
	v_add_f32_e32 v3, 1.0, v2
	v_cmp_gt_f32_e32 vcc, s28, v3
	v_add_f32_e32 v0, v19, v43
	v_mul_f32_e32 v0, 0xbfb8aa3b, v0
	v_cndmask_b32_e64 v16, 0, 32, vcc
	v_ldexp_f32 v3, v3, v16
	v_log_f32_e32 v3, v3
	v_exp_f32_e32 v0, v0
	v_mul_f32_e32 v1, 0xbfb8aa3b, v1
	v_exp_f32_e32 v1, v1
	v_mul_f32_e32 v16, 0x3f317217, v3
	v_fma_f32 v16, v3, s0, -v16
	v_fmac_f32_e32 v16, 0x3377d1cf, v3
	v_fmac_f32_e32 v16, 0x3f317217, v3
	v_cmp_lt_f32_e64 s[6:7], |v3|, s1
	v_add_f32_e32 v0, 1.0, v0
	v_rcp_f32_e32 v0, v0
	v_cndmask_b32_e64 v3, v3, v16, s[6:7]
	v_cndmask_b32_e32 v16, 0, v201, vcc
	v_sub_f32_e32 v3, v3, v16
	v_fmamk_f32 v16, v2, 0xbe800000, v188
	v_fma_f32 v16, -v2, v16, 0.5
	v_fma_f32 v16, -v2, v16, 1.0
	v_mul_f32_e32 v16, v2, v16
	v_cmp_gt_f32_e64 s[6:7], s3, v2
	v_cmp_gt_f32_e32 vcc, s2, v63
	v_mul_f32_e32 v0, 0xc1000000, v0
	v_cndmask_b32_e64 v2, v3, v16, s[6:7]
	v_cndmask_b32_e64 v2, v2, -v63, vcc
	v_mul_f32_e32 v0, v0, v2
	v_mul_f32_e32 v2, 0x3fb8aa3b, v0
	v_add_f32_e32 v0, v0, v0
	v_mul_f32_e32 v3, 0x3fb8aa3b, v0
	v_exp_f32_e32 v142, v2
	v_fmamk_f32 v2, v0, 0x3c088889, v189
	v_exp_f32_e32 v3, v3
	v_fmaak_f32 v2, v0, v2, 0x3e2aaaab
	v_fma_f32 v2, v0, v2, 0.5
	v_fma_f32 v2, v0, v2, 1.0
	v_add_f32_e32 v1, 1.0, v1
	v_mul_f32_e64 v2, v2, -v0
	v_sub_f32_e32 v3, 1.0, v3
	v_cmp_lt_f32_e32 vcc, s4, v0
	v_rcp_f32_e32 v1, v1
	s_nop 0
	v_cndmask_b32_e32 v0, v3, v2, vcc
	v_sqrt_f32_e32 v0, v0
	v_mul_f32_e32 v1, v67, v1
	v_mul_f32_e32 v143, v1, v0
	global_load_dwordx4 v[36:39], v168, s[10:11] offset:32
	global_load_dwordx4 v[16:19], v168, s[12:13] offset:32
	global_load_dwordx4 v[0:3], v168, s[8:9] offset:32
	s_waitcnt vmcnt(2)
	v_add_f32_e32 v20, v20, v36
	v_mul_f32_e32 v20, 0xbfb8aa3b, v20
	v_exp_f32_e32 v20, v20
	s_waitcnt vmcnt(1)
	v_add_f32_e32 v4, v4, v16
	v_mul_f32_e32 v4, 0xbfb8aa3b, v4
	v_exp_f32_e32 v4, v4
	v_add_f32_e32 v20, 1.0, v20
	s_waitcnt vmcnt(0)
	v_mul_f32_e32 v16, 0xbfb8aa3b, v0
	v_rcp_f32_e32 v20, v20
	v_exp_f32_e32 v16, v16
	v_add_f32_e32 v4, 1.0, v4
	v_rcp_f32_e32 v60, v4
	v_mul_f32_e32 v4, 0xc1000000, v20
	v_add_f32_e32 v20, 1.0, v16
	v_cmp_gt_f32_e32 vcc, s28, v20
	s_nop 1
	v_cndmask_b32_e64 v36, 0, 32, vcc
	v_ldexp_f32 v20, v20, v36
	v_log_f32_e32 v20, v20
	s_nop 0
	v_mul_f32_e32 v36, 0x3f317217, v20
	v_fma_f32 v36, v20, s0, -v36
	v_fmac_f32_e32 v36, 0x3377d1cf, v20
	v_fmac_f32_e32 v36, 0x3f317217, v20
	v_cmp_lt_f32_e64 s[6:7], |v20|, s1
	s_nop 1
	v_cndmask_b32_e64 v20, v20, v36, s[6:7]
	v_cndmask_b32_e32 v36, 0, v201, vcc
	v_sub_f32_e32 v20, v20, v36
	v_fmamk_f32 v36, v16, 0xbe800000, v188
	v_fma_f32 v36, -v16, v36, 0.5
	v_fma_f32 v36, -v16, v36, 1.0
	v_mul_f32_e32 v36, v16, v36
	v_cmp_gt_f32_e64 s[6:7], s3, v16
	v_cmp_gt_f32_e32 vcc, s2, v0
	s_nop 0
	v_cndmask_b32_e64 v16, v20, v36, s[6:7]
	v_cndmask_b32_e64 v0, v16, -v0, vcc
	v_mul_f32_e32 v0, v4, v0
	v_mul_f32_e32 v4, 0x3fb8aa3b, v0
	v_add_f32_e32 v0, v0, v0
	v_mul_f32_e32 v16, 0x3fb8aa3b, v0
	v_exp_f32_e32 v62, v4
	v_fmamk_f32 v4, v0, 0x3c088889, v189
	v_exp_f32_e32 v16, v16
	v_fmaak_f32 v4, v0, v4, 0x3e2aaaab
	v_fma_f32 v4, v0, v4, 0.5
	v_fma_f32 v4, v0, v4, 1.0
	v_mul_f32_e64 v4, v4, -v0
	v_sub_f32_e32 v16, 1.0, v16
	v_cmp_lt_f32_e32 vcc, s4, v0
	s_nop 1
	v_cndmask_b32_e32 v0, v16, v4, vcc
	v_add_f32_e32 v4, v5, v17
	v_mul_f32_e32 v4, 0xbfb8aa3b, v4
	v_exp_f32_e32 v4, v4
	v_sqrt_f32_e32 v64, v0
	v_add_f32_e32 v0, v21, v37
	v_mul_f32_e32 v0, 0xbfb8aa3b, v0
	v_add_f32_e32 v4, 1.0, v4
	v_rcp_f32_e32 v61, v4
	v_mul_f32_e32 v4, 0xbfb8aa3b, v1
	v_exp_f32_e32 v4, v4
	v_exp_f32_e32 v0, v0
	v_add_f32_e32 v5, 1.0, v4
	v_cmp_gt_f32_e32 vcc, s28, v5
	v_add_f32_e32 v0, 1.0, v0
	v_rcp_f32_e32 v0, v0
	v_cndmask_b32_e64 v16, 0, 32, vcc
	v_ldexp_f32 v5, v5, v16
	v_log_f32_e32 v5, v5
	v_mul_f32_e32 v0, 0xc1000000, v0
	v_mul_f32_e32 v16, 0x3f317217, v5
	v_fma_f32 v16, v5, s0, -v16
	v_fmac_f32_e32 v16, 0x3377d1cf, v5
	v_fmac_f32_e32 v16, 0x3f317217, v5
	v_cmp_lt_f32_e64 s[6:7], |v5|, s1
	s_nop 1
	v_cndmask_b32_e64 v5, v5, v16, s[6:7]
	v_cndmask_b32_e32 v16, 0, v201, vcc
	v_sub_f32_e32 v5, v5, v16
	v_fmamk_f32 v16, v4, 0xbe800000, v188
	v_fma_f32 v16, -v4, v16, 0.5
	v_fma_f32 v16, -v4, v16, 1.0
	v_mul_f32_e32 v16, v4, v16
	v_cmp_gt_f32_e64 s[6:7], s3, v4
	v_cmp_gt_f32_e32 vcc, s2, v1
	s_nop 0
	v_cndmask_b32_e64 v4, v5, v16, s[6:7]
	v_cndmask_b32_e64 v1, v4, -v1, vcc
	v_mul_f32_e32 v0, v0, v1
	v_mul_f32_e32 v1, 0x3fb8aa3b, v0
	v_add_f32_e32 v0, v0, v0
	v_mul_f32_e32 v4, 0x3fb8aa3b, v0
	v_exp_f32_e32 v63, v1
	v_fmamk_f32 v1, v0, 0x3c088889, v189
	v_exp_f32_e32 v4, v4
	v_fmaak_f32 v1, v0, v1, 0x3e2aaaab
	v_fma_f32 v1, v0, v1, 0.5
	v_fma_f32 v1, v0, v1, 1.0
	v_mul_f32_e64 v1, v1, -v0
	v_sub_f32_e32 v4, 1.0, v4
	v_cmp_lt_f32_e32 vcc, s4, v0
	s_nop 1
	v_cndmask_b32_e32 v0, v4, v1, vcc
	v_add_f32_e32 v1, v6, v18
	v_mul_f32_e32 v1, 0xbfb8aa3b, v1
	v_exp_f32_e32 v1, v1
	v_sqrt_f32_e32 v65, v0
	v_add_f32_e32 v0, v22, v38
	v_mul_f32_e32 v0, 0xbfb8aa3b, v0
	v_add_f32_e32 v1, 1.0, v1
	v_rcp_f32_e32 v66, v1
	v_mul_f32_e32 v1, 0xbfb8aa3b, v2
	v_exp_f32_e32 v1, v1
	v_exp_f32_e32 v0, v0
	v_add_f32_e32 v4, 1.0, v1
	v_cmp_gt_f32_e32 vcc, s28, v4
	v_add_f32_e32 v0, 1.0, v0
	v_rcp_f32_e32 v0, v0
	v_cndmask_b32_e64 v5, 0, 32, vcc
	v_ldexp_f32 v4, v4, v5
	v_log_f32_e32 v4, v4
	v_mul_f32_e32 v0, 0xc1000000, v0
	v_mul_f32_e32 v5, 0x3f317217, v4
	v_fma_f32 v5, v4, s0, -v5
	v_fmac_f32_e32 v5, 0x3377d1cf, v4
	v_fmac_f32_e32 v5, 0x3f317217, v4
	v_cmp_lt_f32_e64 s[6:7], |v4|, s1
	s_nop 1
	v_cndmask_b32_e64 v4, v4, v5, s[6:7]
	v_cndmask_b32_e32 v5, 0, v201, vcc
	v_sub_f32_e32 v4, v4, v5
	v_fmamk_f32 v5, v1, 0xbe800000, v188
	v_fma_f32 v5, -v1, v5, 0.5
	v_fma_f32 v5, -v1, v5, 1.0
	v_mul_f32_e32 v5, v1, v5
	v_cmp_gt_f32_e64 s[6:7], s3, v1
	v_cmp_gt_f32_e32 vcc, s2, v2
	s_nop 0
	v_cndmask_b32_e64 v1, v4, v5, s[6:7]
	v_cndmask_b32_e64 v1, v1, -v2, vcc
	v_mul_f32_e32 v0, v0, v1
	v_mul_f32_e32 v1, 0x3fb8aa3b, v0
	v_add_f32_e32 v0, v0, v0
	v_mul_f32_e32 v2, 0x3fb8aa3b, v0
	v_exp_f32_e32 v68, v1
	v_fmamk_f32 v1, v0, 0x3c088889, v189
	v_exp_f32_e32 v2, v2
	v_fmaak_f32 v1, v0, v1, 0x3e2aaaab
	v_fma_f32 v1, v0, v1, 0.5
	v_fma_f32 v1, v0, v1, 1.0
	v_mul_f32_e64 v1, v1, -v0
	v_sub_f32_e32 v2, 1.0, v2
	v_cmp_lt_f32_e32 vcc, s4, v0
	s_nop 1
	v_cndmask_b32_e32 v0, v2, v1, vcc
	v_add_f32_e32 v1, v7, v19
	v_mul_f32_e32 v1, 0xbfb8aa3b, v1
	v_exp_f32_e32 v1, v1
	v_sqrt_f32_e32 v70, v0
	v_add_f32_e32 v0, v23, v39
	v_mul_f32_e32 v0, 0xbfb8aa3b, v0
	v_add_f32_e32 v1, 1.0, v1
	v_rcp_f32_e32 v67, v1
	v_mul_f32_e32 v1, 0xbfb8aa3b, v3
	v_exp_f32_e32 v1, v1
	v_exp_f32_e32 v0, v0
	v_add_f32_e32 v2, 1.0, v1
	v_cmp_gt_f32_e32 vcc, s28, v2
	v_add_f32_e32 v0, 1.0, v0
	v_rcp_f32_e32 v0, v0
	v_cndmask_b32_e64 v4, 0, 32, vcc
	v_ldexp_f32 v2, v2, v4
	v_log_f32_e32 v2, v2
	v_mul_f32_e32 v0, 0xc1000000, v0
	v_mul_f32_e32 v4, 0x3f317217, v2
	v_fma_f32 v4, v2, s0, -v4
	v_fmac_f32_e32 v4, 0x3377d1cf, v2
	v_fmac_f32_e32 v4, 0x3f317217, v2
	v_cmp_lt_f32_e64 s[6:7], |v2|, s1
	s_nop 1
	v_cndmask_b32_e64 v2, v2, v4, s[6:7]
	v_cndmask_b32_e32 v4, 0, v201, vcc
	v_sub_f32_e32 v2, v2, v4
	v_fmamk_f32 v4, v1, 0xbe800000, v188
	v_fma_f32 v4, -v1, v4, 0.5
	v_fma_f32 v4, -v1, v4, 1.0
	v_mul_f32_e32 v4, v1, v4
	v_cmp_gt_f32_e64 s[6:7], s3, v1
	v_cmp_gt_f32_e32 vcc, s2, v3
	s_nop 0
	v_cndmask_b32_e64 v1, v2, v4, s[6:7]
	v_cndmask_b32_e64 v1, v1, -v3, vcc
	v_mul_f32_e32 v0, v0, v1
	v_mul_f32_e32 v1, 0x3fb8aa3b, v0
	v_add_f32_e32 v0, v0, v0
	v_mul_f32_e32 v2, 0x3fb8aa3b, v0
	v_exp_f32_e32 v69, v1
	v_fmamk_f32 v1, v0, 0x3c088889, v189
	v_exp_f32_e32 v2, v2
	v_fmaak_f32 v1, v0, v1, 0x3e2aaaab
	v_fma_f32 v1, v0, v1, 0.5
	v_fma_f32 v1, v0, v1, 1.0
	v_mul_f32_e64 v1, v1, -v0
	v_sub_f32_e32 v2, 1.0, v2
	v_cmp_lt_f32_e32 vcc, s4, v0
	s_nop 1
	v_cndmask_b32_e32 v0, v2, v1, vcc
	v_sqrt_f32_e32 v71, v0
	global_load_dwordx4 v[0:3], v168, s[10:11] offset:64
	global_load_dwordx4 v[4:7], v168, s[12:13] offset:64
	global_load_dwordx4 v[16:19], v168, s[8:9] offset:64
	ds_read_b128 v[36:39], v124 offset:64
	s_waitcnt vmcnt(2)
	v_add_f32_e32 v0, v24, v0
	s_waitcnt vmcnt(1)
	v_add_f32_e32 v4, v8, v4
	v_mul_f32_e32 v4, 0xbfb8aa3b, v4
	v_exp_f32_e32 v4, v4
	v_mul_f32_e32 v0, 0xbfb8aa3b, v0
	v_exp_f32_e32 v0, v0
	v_add_f32_e32 v4, 1.0, v4
	v_rcp_f32_e32 v72, v4
	s_waitcnt vmcnt(0)
	v_mul_f32_e32 v4, 0xbfb8aa3b, v16
	v_exp_f32_e32 v4, v4
	v_add_f32_e32 v0, 1.0, v0
	v_rcp_f32_e32 v0, v0
	v_add_f32_e32 v8, 1.0, v4
	v_cmp_gt_f32_e32 vcc, s28, v8
	v_mul_f32_e32 v0, 0xc1000000, v0
	s_nop 0
	v_cndmask_b32_e64 v20, 0, 32, vcc
	v_ldexp_f32 v8, v8, v20
	v_log_f32_e32 v8, v8
	s_nop 0
	v_mul_f32_e32 v20, 0x3f317217, v8
	v_fma_f32 v20, v8, s0, -v20
	v_fmac_f32_e32 v20, 0x3377d1cf, v8
	v_fmac_f32_e32 v20, 0x3f317217, v8
	v_cmp_lt_f32_e64 s[6:7], |v8|, s1
	s_nop 1
	v_cndmask_b32_e64 v8, v8, v20, s[6:7]
	v_cndmask_b32_e32 v20, 0, v201, vcc
	v_sub_f32_e32 v8, v8, v20
	v_fmamk_f32 v20, v4, 0xbe800000, v188
	v_fma_f32 v20, -v4, v20, 0.5
	v_fma_f32 v20, -v4, v20, 1.0
	v_mul_f32_e32 v20, v4, v20
	v_cmp_gt_f32_e64 s[6:7], s3, v4
	v_cmp_gt_f32_e32 vcc, s2, v16
	s_nop 0
	v_cndmask_b32_e64 v4, v8, v20, s[6:7]
	v_cndmask_b32_e64 v4, v4, -v16, vcc
	v_mul_f32_e32 v0, v0, v4
	v_mul_f32_e32 v4, 0x3fb8aa3b, v0
	v_add_f32_e32 v0, v0, v0
	v_mul_f32_e32 v8, 0x3fb8aa3b, v0
	v_exp_f32_e32 v76, v4
	v_fmamk_f32 v4, v0, 0x3c088889, v189
	v_exp_f32_e32 v8, v8
	v_fmaak_f32 v4, v0, v4, 0x3e2aaaab
	v_fma_f32 v4, v0, v4, 0.5
	v_fma_f32 v4, v0, v4, 1.0
	v_mul_f32_e64 v4, v4, -v0
	v_sub_f32_e32 v8, 1.0, v8
	v_cmp_lt_f32_e32 vcc, s4, v0
	s_nop 1
	v_cndmask_b32_e32 v0, v8, v4, vcc
	v_sqrt_f32_e32 v80, v0
	v_add_f32_e32 v0, v25, v1
	v_add_f32_e32 v1, v9, v5
	v_mul_f32_e32 v1, 0xbfb8aa3b, v1
	v_exp_f32_e32 v1, v1
	v_mul_f32_e32 v0, 0xbfb8aa3b, v0
	v_exp_f32_e32 v0, v0
	v_add_f32_e32 v1, 1.0, v1
	v_rcp_f32_e32 v73, v1
	v_mul_f32_e32 v1, 0xbfb8aa3b, v17
	v_exp_f32_e32 v1, v1
	v_add_f32_e32 v0, 1.0, v0
	v_rcp_f32_e32 v0, v0
	v_add_f32_e32 v4, 1.0, v1
	v_cmp_gt_f32_e32 vcc, s28, v4
	v_mul_f32_e32 v0, 0xc1000000, v0
	s_nop 0
	v_cndmask_b32_e64 v5, 0, 32, vcc
	v_ldexp_f32 v4, v4, v5
	v_log_f32_e32 v4, v4
	s_nop 0
	v_mul_f32_e32 v5, 0x3f317217, v4
	v_fma_f32 v5, v4, s0, -v5
	v_fmac_f32_e32 v5, 0x3377d1cf, v4
	v_fmac_f32_e32 v5, 0x3f317217, v4
	v_cmp_lt_f32_e64 s[6:7], |v4|, s1
	s_nop 1
	v_cndmask_b32_e64 v4, v4, v5, s[6:7]
	v_cndmask_b32_e32 v5, 0, v201, vcc
	v_sub_f32_e32 v4, v4, v5
	v_fmamk_f32 v5, v1, 0xbe800000, v188
	v_fma_f32 v5, -v1, v5, 0.5
	v_fma_f32 v5, -v1, v5, 1.0
	v_mul_f32_e32 v5, v1, v5
	v_cmp_gt_f32_e64 s[6:7], s3, v1
	v_cmp_gt_f32_e32 vcc, s2, v17
	s_nop 0
	v_cndmask_b32_e64 v1, v4, v5, s[6:7]
	v_cndmask_b32_e64 v1, v1, -v17, vcc
	v_mul_f32_e32 v0, v0, v1
	v_mul_f32_e32 v1, 0x3fb8aa3b, v0
	v_add_f32_e32 v0, v0, v0
	v_mul_f32_e32 v4, 0x3fb8aa3b, v0
	v_exp_f32_e32 v77, v1
	v_fmamk_f32 v1, v0, 0x3c088889, v189
	v_exp_f32_e32 v4, v4
	v_fmaak_f32 v1, v0, v1, 0x3e2aaaab
	v_fma_f32 v1, v0, v1, 0.5
	v_fma_f32 v1, v0, v1, 1.0
	v_mul_f32_e64 v1, v1, -v0
	v_sub_f32_e32 v4, 1.0, v4
	v_cmp_lt_f32_e32 vcc, s4, v0
	s_nop 1
	v_cndmask_b32_e32 v0, v4, v1, vcc
	v_add_f32_e32 v1, v10, v6
	v_mul_f32_e32 v1, 0xbfb8aa3b, v1
	v_exp_f32_e32 v1, v1
	v_sqrt_f32_e32 v81, v0
	v_add_f32_e32 v0, v26, v2
	v_mul_f32_e32 v0, 0xbfb8aa3b, v0
	v_add_f32_e32 v1, 1.0, v1
	v_rcp_f32_e32 v74, v1
	v_mul_f32_e32 v1, 0xbfb8aa3b, v18
	v_exp_f32_e32 v1, v1
	v_exp_f32_e32 v0, v0
	v_add_f32_e32 v2, 1.0, v1
	v_cmp_gt_f32_e32 vcc, s28, v2
	v_add_f32_e32 v0, 1.0, v0
	v_rcp_f32_e32 v0, v0
	v_cndmask_b32_e64 v4, 0, 32, vcc
	v_ldexp_f32 v2, v2, v4
	v_log_f32_e32 v2, v2
	v_mul_f32_e32 v0, 0xc1000000, v0
	v_mul_f32_e32 v4, 0x3f317217, v2
	v_fma_f32 v4, v2, s0, -v4
	v_fmac_f32_e32 v4, 0x3377d1cf, v2
	v_fmac_f32_e32 v4, 0x3f317217, v2
	v_cmp_lt_f32_e64 s[6:7], |v2|, s1
	s_nop 1
	v_cndmask_b32_e64 v2, v2, v4, s[6:7]
	v_cndmask_b32_e32 v4, 0, v201, vcc
	v_sub_f32_e32 v2, v2, v4
	v_fmamk_f32 v4, v1, 0xbe800000, v188
	v_fma_f32 v4, -v1, v4, 0.5
	v_fma_f32 v4, -v1, v4, 1.0
	v_mul_f32_e32 v4, v1, v4
	v_cmp_gt_f32_e64 s[6:7], s3, v1
	v_cmp_gt_f32_e32 vcc, s2, v18
	s_nop 0
	v_cndmask_b32_e64 v1, v2, v4, s[6:7]
	v_cndmask_b32_e64 v1, v1, -v18, vcc
	v_mul_f32_e32 v0, v0, v1
	v_mul_f32_e32 v1, 0x3fb8aa3b, v0
	v_add_f32_e32 v0, v0, v0
	v_mul_f32_e32 v2, 0x3fb8aa3b, v0
	v_exp_f32_e32 v78, v1
	v_fmamk_f32 v1, v0, 0x3c088889, v189
	v_exp_f32_e32 v2, v2
	v_fmaak_f32 v1, v0, v1, 0x3e2aaaab
	v_fma_f32 v1, v0, v1, 0.5
	v_fma_f32 v1, v0, v1, 1.0
	v_mul_f32_e64 v1, v1, -v0
	v_sub_f32_e32 v2, 1.0, v2
	v_cmp_lt_f32_e32 vcc, s4, v0
	s_nop 1
	v_cndmask_b32_e32 v0, v2, v1, vcc
	v_add_f32_e32 v1, v11, v7
	v_mul_f32_e32 v1, 0xbfb8aa3b, v1
	v_exp_f32_e32 v1, v1
	v_sqrt_f32_e32 v82, v0
	v_add_f32_e32 v0, v27, v3
	v_mul_f32_e32 v0, 0xbfb8aa3b, v0
	v_add_f32_e32 v1, 1.0, v1
	v_rcp_f32_e32 v75, v1
	v_mul_f32_e32 v1, 0xbfb8aa3b, v19
	v_exp_f32_e32 v1, v1
	v_exp_f32_e32 v0, v0
	v_add_f32_e32 v2, 1.0, v1
	v_cmp_gt_f32_e32 vcc, s28, v2
	v_add_f32_e32 v0, 1.0, v0
	v_rcp_f32_e32 v0, v0
	v_cndmask_b32_e64 v3, 0, 32, vcc
	v_ldexp_f32 v2, v2, v3
	v_log_f32_e32 v2, v2
	v_mul_f32_e32 v0, 0xc1000000, v0
	v_mul_f32_e32 v3, 0x3f317217, v2
	v_fma_f32 v3, v2, s0, -v3
	v_fmac_f32_e32 v3, 0x3377d1cf, v2
	v_fmac_f32_e32 v3, 0x3f317217, v2
	v_cmp_lt_f32_e64 s[6:7], |v2|, s1
	s_nop 1
	v_cndmask_b32_e64 v2, v2, v3, s[6:7]
	v_cndmask_b32_e32 v3, 0, v201, vcc
	v_sub_f32_e32 v2, v2, v3
	v_fmamk_f32 v3, v1, 0xbe800000, v188
	v_fma_f32 v3, -v1, v3, 0.5
	v_fma_f32 v3, -v1, v3, 1.0
	v_mul_f32_e32 v3, v1, v3
	v_cmp_gt_f32_e64 s[6:7], s3, v1
	v_cmp_gt_f32_e32 vcc, s2, v19
	s_nop 0
	v_cndmask_b32_e64 v1, v2, v3, s[6:7]
	v_cndmask_b32_e64 v1, v1, -v19, vcc
	v_mul_f32_e32 v0, v0, v1
	v_mul_f32_e32 v1, 0x3fb8aa3b, v0
	v_add_f32_e32 v0, v0, v0
	v_mul_f32_e32 v2, 0x3fb8aa3b, v0
	v_exp_f32_e32 v79, v1
	v_fmamk_f32 v1, v0, 0x3c088889, v189
	v_exp_f32_e32 v2, v2
	v_fmaak_f32 v1, v0, v1, 0x3e2aaaab
	v_fma_f32 v1, v0, v1, 0.5
	v_fma_f32 v1, v0, v1, 1.0
	v_mul_f32_e64 v1, v1, -v0
	v_sub_f32_e32 v2, 1.0, v2
	v_cmp_lt_f32_e32 vcc, s4, v0
	s_nop 1
	v_cndmask_b32_e32 v0, v2, v1, vcc
	v_sqrt_f32_e32 v83, v0
	global_load_dwordx4 v[4:7], v168, s[10:11] offset:96
	global_load_dwordx4 v[0:3], v168, s[12:13] offset:96
	global_load_dwordx4 v[8:11], v168, s[8:9] offset:96
	ds_read_b128 v[40:43], v124 offset:96
	s_waitcnt vmcnt(2)
	v_add_f32_e32 v4, v28, v4
	v_mul_f32_e32 v4, 0xbfb8aa3b, v4
	v_exp_f32_e32 v4, v4
	s_waitcnt vmcnt(1)
	v_add_f32_e32 v0, v12, v0
	v_mul_f32_e32 v0, 0xbfb8aa3b, v0
	v_exp_f32_e32 v0, v0
	v_add_f32_e32 v4, 1.0, v4
	v_rcp_f32_e32 v4, v4
	v_add_f32_e32 v1, v13, v1
	v_add_f32_e32 v0, 1.0, v0
	v_rcp_f32_e32 v84, v0
	v_mul_f32_e32 v0, 0xc1000000, v4
	s_waitcnt vmcnt(0)
	v_mul_f32_e32 v4, 0xbfb8aa3b, v8
	v_exp_f32_e32 v4, v4
	v_mul_f32_e32 v1, 0xbfb8aa3b, v1
	v_exp_f32_e32 v1, v1
	v_add_f32_e32 v12, 1.0, v4
	v_cmp_gt_f32_e32 vcc, s28, v12
	v_add_f32_e32 v1, 1.0, v1
	v_rcp_f32_e32 v85, v1
	v_cndmask_b32_e64 v16, 0, 32, vcc
	v_ldexp_f32 v12, v12, v16
	v_log_f32_e32 v12, v12
	v_mul_f32_e32 v1, 0xbfb8aa3b, v9
	v_exp_f32_e32 v1, v1
	v_mul_f32_e32 v16, 0x3f317217, v12
	v_fma_f32 v16, v12, s0, -v16
	v_fmac_f32_e32 v16, 0x3377d1cf, v12
	v_fmac_f32_e32 v16, 0x3f317217, v12
	v_cmp_lt_f32_e64 s[6:7], |v12|, s1
	s_nop 1
	v_cndmask_b32_e64 v12, v12, v16, s[6:7]
	v_cndmask_b32_e32 v16, 0, v201, vcc
	v_sub_f32_e32 v12, v12, v16
	v_fmamk_f32 v16, v4, 0xbe800000, v188
	v_fma_f32 v16, -v4, v16, 0.5
	v_fma_f32 v16, -v4, v16, 1.0
	v_mul_f32_e32 v16, v4, v16
	v_cmp_gt_f32_e64 s[6:7], s3, v4
	v_cmp_gt_f32_e32 vcc, s2, v8
	s_nop 0
	v_cndmask_b32_e64 v4, v12, v16, s[6:7]
	v_cndmask_b32_e64 v4, v4, -v8, vcc
	v_mul_f32_e32 v0, v0, v4
	v_mul_f32_e32 v4, 0x3fb8aa3b, v0
	v_add_f32_e32 v0, v0, v0
	v_mul_f32_e32 v8, 0x3fb8aa3b, v0
	v_exp_f32_e32 v86, v4
	v_fmamk_f32 v4, v0, 0x3c088889, v189
	v_exp_f32_e32 v8, v8
	v_fmaak_f32 v4, v0, v4, 0x3e2aaaab
	v_fma_f32 v4, v0, v4, 0.5
	v_fma_f32 v4, v0, v4, 1.0
	v_mul_f32_e64 v4, v4, -v0
	v_sub_f32_e32 v8, 1.0, v8
	v_cmp_lt_f32_e32 vcc, s4, v0
	s_nop 1
	v_cndmask_b32_e32 v0, v8, v4, vcc
	v_add_f32_e32 v4, 1.0, v1
	v_cmp_gt_f32_e32 vcc, s28, v4
	v_sqrt_f32_e32 v88, v0
	v_add_f32_e32 v0, v29, v5
	v_cndmask_b32_e64 v5, 0, 32, vcc
	v_ldexp_f32 v4, v4, v5
	v_log_f32_e32 v4, v4
	v_mul_f32_e32 v0, 0xbfb8aa3b, v0
	v_exp_f32_e32 v0, v0
	v_mul_f32_e32 v5, 0x3f317217, v4
	v_fma_f32 v5, v4, s0, -v5
	v_fmac_f32_e32 v5, 0x3377d1cf, v4
	v_fmac_f32_e32 v5, 0x3f317217, v4
	v_cmp_lt_f32_e64 s[6:7], |v4|, s1
	v_add_f32_e32 v0, 1.0, v0
	v_rcp_f32_e32 v0, v0
	v_cndmask_b32_e64 v4, v4, v5, s[6:7]
	v_cndmask_b32_e32 v5, 0, v201, vcc
	v_sub_f32_e32 v4, v4, v5
	v_fmamk_f32 v5, v1, 0xbe800000, v188
	v_fma_f32 v5, -v1, v5, 0.5
	v_fma_f32 v5, -v1, v5, 1.0
	v_mul_f32_e32 v5, v1, v5
	v_cmp_gt_f32_e64 s[6:7], s3, v1
	v_cmp_gt_f32_e32 vcc, s2, v9
	v_mul_f32_e32 v0, 0xc1000000, v0
	v_cndmask_b32_e64 v1, v4, v5, s[6:7]
	v_cndmask_b32_e64 v1, v1, -v9, vcc
	v_mul_f32_e32 v0, v0, v1
	v_mul_f32_e32 v1, 0x3fb8aa3b, v0
	v_add_f32_e32 v0, v0, v0
	v_mul_f32_e32 v4, 0x3fb8aa3b, v0
	v_exp_f32_e32 v87, v1
	v_fmamk_f32 v1, v0, 0x3c088889, v189
	v_exp_f32_e32 v4, v4
	v_fmaak_f32 v1, v0, v1, 0x3e2aaaab
	v_fma_f32 v1, v0, v1, 0.5
	v_fma_f32 v1, v0, v1, 1.0
	v_mul_f32_e64 v1, v1, -v0
	v_sub_f32_e32 v4, 1.0, v4
	v_cmp_lt_f32_e32 vcc, s4, v0
	s_nop 1
	v_cndmask_b32_e32 v0, v4, v1, vcc
	v_add_f32_e32 v1, v14, v2
	v_mul_f32_e32 v1, 0xbfb8aa3b, v1
	v_exp_f32_e32 v1, v1
	v_sqrt_f32_e32 v89, v0
	v_add_f32_e32 v0, v30, v6
	v_mul_f32_e32 v0, 0xbfb8aa3b, v0
	v_add_f32_e32 v1, 1.0, v1
	v_rcp_f32_e32 v90, v1
	v_mul_f32_e32 v1, 0xbfb8aa3b, v10
	v_exp_f32_e32 v1, v1
	v_exp_f32_e32 v0, v0
	v_add_f32_e32 v2, 1.0, v1
	v_cmp_gt_f32_e32 vcc, s28, v2
	v_add_f32_e32 v0, 1.0, v0
	v_rcp_f32_e32 v0, v0
	v_cndmask_b32_e64 v4, 0, 32, vcc
	v_ldexp_f32 v2, v2, v4
	v_log_f32_e32 v2, v2
	v_mul_f32_e32 v0, 0xc1000000, v0
	v_mul_f32_e32 v4, 0x3f317217, v2
	v_fma_f32 v4, v2, s0, -v4
	v_fmac_f32_e32 v4, 0x3377d1cf, v2
	v_fmac_f32_e32 v4, 0x3f317217, v2
	v_cmp_lt_f32_e64 s[6:7], |v2|, s1
	s_nop 1
	v_cndmask_b32_e64 v2, v2, v4, s[6:7]
	v_cndmask_b32_e32 v4, 0, v201, vcc
	v_sub_f32_e32 v2, v2, v4
	v_fmamk_f32 v4, v1, 0xbe800000, v188
	v_fma_f32 v4, -v1, v4, 0.5
	v_fma_f32 v4, -v1, v4, 1.0
	v_mul_f32_e32 v4, v1, v4
	v_cmp_gt_f32_e64 s[6:7], s3, v1
	v_cmp_gt_f32_e32 vcc, s2, v10
	s_nop 0
	v_cndmask_b32_e64 v1, v2, v4, s[6:7]
	v_cndmask_b32_e64 v1, v1, -v10, vcc
	v_mul_f32_e32 v0, v0, v1
	v_mul_f32_e32 v1, 0x3fb8aa3b, v0
	v_add_f32_e32 v0, v0, v0
	v_mul_f32_e32 v2, 0x3fb8aa3b, v0
	v_exp_f32_e32 v92, v1
	v_fmamk_f32 v1, v0, 0x3c088889, v189
	v_exp_f32_e32 v2, v2
	v_fmaak_f32 v1, v0, v1, 0x3e2aaaab
	v_fma_f32 v1, v0, v1, 0.5
	v_fma_f32 v1, v0, v1, 1.0
	v_mul_f32_e64 v1, v1, -v0
	v_sub_f32_e32 v2, 1.0, v2
	v_cmp_lt_f32_e32 vcc, s4, v0
	s_nop 1
	v_cndmask_b32_e32 v0, v2, v1, vcc
	v_add_f32_e32 v1, v15, v3
	v_mul_f32_e32 v1, 0xbfb8aa3b, v1
	v_exp_f32_e32 v1, v1
	v_sqrt_f32_e32 v94, v0
	v_add_f32_e32 v0, v31, v7
	v_mul_f32_e32 v0, 0xbfb8aa3b, v0
	v_add_f32_e32 v1, 1.0, v1
	v_rcp_f32_e32 v91, v1
	v_mul_f32_e32 v1, 0xbfb8aa3b, v11
	v_exp_f32_e32 v1, v1
	v_exp_f32_e32 v0, v0
	v_add_f32_e32 v2, 1.0, v1
	v_cmp_gt_f32_e32 vcc, s28, v2
	v_add_f32_e32 v0, 1.0, v0
	v_rcp_f32_e32 v0, v0
	v_cndmask_b32_e64 v3, 0, 32, vcc
	v_ldexp_f32 v2, v2, v3
	v_log_f32_e32 v2, v2
	v_mul_f32_e32 v0, 0xc1000000, v0
	v_mul_f32_e32 v3, 0x3f317217, v2
	v_fma_f32 v3, v2, s0, -v3
	v_fmac_f32_e32 v3, 0x3377d1cf, v2
	v_fmac_f32_e32 v3, 0x3f317217, v2
	v_cmp_lt_f32_e64 s[6:7], |v2|, s1
	s_nop 1
	v_cndmask_b32_e64 v2, v2, v3, s[6:7]
	v_cndmask_b32_e32 v3, 0, v201, vcc
	v_sub_f32_e32 v2, v2, v3
	v_fmamk_f32 v3, v1, 0xbe800000, v188
	v_fma_f32 v3, -v1, v3, 0.5
	v_fma_f32 v3, -v1, v3, 1.0
	v_mul_f32_e32 v3, v1, v3
	v_cmp_gt_f32_e64 s[6:7], s3, v1
	v_cmp_gt_f32_e32 vcc, s2, v11
	s_nop 0
	v_cndmask_b32_e64 v1, v2, v3, s[6:7]
	v_cndmask_b32_e64 v1, v1, -v11, vcc
	v_mul_f32_e32 v0, v0, v1
	v_mul_f32_e32 v1, 0x3fb8aa3b, v0
	v_add_f32_e32 v0, v0, v0
	v_mul_f32_e32 v2, 0x3fb8aa3b, v0
	v_exp_f32_e32 v93, v1
	v_fmamk_f32 v1, v0, 0x3c088889, v189
	v_exp_f32_e32 v2, v2
	v_fmaak_f32 v1, v0, v1, 0x3e2aaaab
	v_fma_f32 v1, v0, v1, 0.5
	v_fma_f32 v1, v0, v1, 1.0
	v_mul_f32_e64 v1, v1, -v0
	v_sub_f32_e32 v2, 1.0, v2
	v_cmp_lt_f32_e32 vcc, s4, v0
	s_nop 1
	v_cndmask_b32_e32 v0, v2, v1, vcc
	v_sqrt_f32_e32 v95, v0
	v_or_b32_e32 v0, 0x1000, v100
	v_mov_b32_e32 v1, v169
	v_lshl_add_u64 v[100:101], v[96:97], 0, v[0:1]
	v_lshl_add_u64 v[102:103], v[98:99], 0, v[0:1]
	global_load_dwordx4 v[0:3], v[100:101], off
	global_load_dwordx4 v[4:7], v[102:103], off
	s_waitcnt vmcnt(1)
	v_mfma_f32_32x32x16_bf16 v[16:31], v[0:3], v[56:59], 0
	s_waitcnt vmcnt(0)
	v_mfma_f32_32x32x16_bf16 v[0:15], v[4:7], v[56:59], 0
	global_load_dwordx4 v[56:59], v[100:101], off offset:32
	global_load_dwordx4 v[96:99], v[102:103], off offset:32
	s_waitcnt vmcnt(1)
	v_mfma_f32_32x32x16_bf16 v[16:31], v[56:59], v[52:55], v[16:31]
	s_waitcnt vmcnt(0)
	v_mfma_f32_32x32x16_bf16 v[0:15], v[96:99], v[52:55], v[0:15]
	global_load_dwordx4 v[52:55], v[100:101], off offset:64
	global_load_dwordx4 v[56:59], v[102:103], off offset:64
	s_waitcnt vmcnt(1)
	v_mfma_f32_32x32x16_bf16 v[16:31], v[52:55], v[48:51], v[16:31]
	s_waitcnt vmcnt(0)
	v_mfma_f32_32x32x16_bf16 v[0:15], v[56:59], v[48:51], v[0:15]
	global_load_dwordx4 v[48:51], v[100:101], off offset:96
	global_load_dwordx4 v[52:55], v[102:103], off offset:96
	s_waitcnt vmcnt(0)
	v_mfma_f32_32x32x16_bf16 v[0:15], v[52:55], v[44:47], v[0:15]
	global_load_dwordx4 v[52:55], v168, s[10:11] offset:128
	global_load_dwordx4 v[56:59], v168, s[12:13] offset:128
	global_load_dwordx4 v[96:99], v168, s[8:9] offset:128
	s_waitcnt vmcnt(1)
	s_nop 7
	v_add_f32_e32 v0, v0, v56
	v_mfma_f32_32x32x16_bf16 v[16:31], v[48:51], v[44:47], v[16:31]
	v_mul_f32_e32 v0, 0xbfb8aa3b, v0
	v_exp_f32_e32 v0, v0
	v_add_f32_e32 v1, v1, v57
	v_mul_f32_e32 v1, 0xbfb8aa3b, v1
	v_exp_f32_e32 v1, v1
	v_add_f32_e32 v0, 1.0, v0
	v_rcp_f32_e32 v56, v0
	s_nop 4
	v_add_f32_e32 v16, v16, v52
	v_mul_f32_e32 v16, 0xbfb8aa3b, v16
	v_exp_f32_e32 v16, v16
	v_add_f32_e32 v1, 1.0, v1
	v_rcp_f32_e32 v57, v1
	s_waitcnt vmcnt(0)
	v_mul_f32_e32 v1, 0xbfb8aa3b, v97
	v_add_f32_e32 v16, 1.0, v16
	v_rcp_f32_e32 v16, v16
	v_exp_f32_e32 v1, v1
	ds_read_b128 v[48:51], v124 offset:128
	ds_read_b128 v[44:47], v124 offset:160
	v_mul_f32_e32 v0, 0xc1000000, v16
	v_mul_f32_e32 v16, 0xbfb8aa3b, v96
	v_exp_f32_e32 v16, v16
	s_nop 0
	v_add_f32_e32 v52, 1.0, v16
	v_cmp_gt_f32_e32 vcc, s28, v52
	s_nop 1
	v_cndmask_b32_e64 v100, 0, 32, vcc
	v_ldexp_f32 v52, v52, v100
	v_log_f32_e32 v52, v52
	s_nop 0
	v_mul_f32_e32 v100, 0x3f317217, v52
	v_fma_f32 v100, v52, s0, -v100
	v_fmac_f32_e32 v100, 0x3377d1cf, v52
	v_fmac_f32_e32 v100, 0x3f317217, v52
	v_cmp_lt_f32_e64 s[6:7], |v52|, s1
	s_nop 1
	v_cndmask_b32_e64 v52, v52, v100, s[6:7]
	v_cndmask_b32_e32 v100, 0, v201, vcc
	v_sub_f32_e32 v52, v52, v100
	v_fmamk_f32 v100, v16, 0xbe800000, v188
	v_fma_f32 v100, -v16, v100, 0.5
	v_fma_f32 v100, -v16, v100, 1.0
	v_mul_f32_e32 v100, v16, v100
	v_cmp_gt_f32_e64 s[6:7], s3, v16
	v_cmp_gt_f32_e32 vcc, s2, v96
	s_nop 0
	v_cndmask_b32_e64 v16, v52, v100, s[6:7]
	v_cndmask_b32_e64 v16, v16, -v96, vcc
	v_mul_f32_e32 v0, v0, v16
	v_mul_f32_e32 v16, 0x3fb8aa3b, v0
	v_add_f32_e32 v0, v0, v0
	v_mul_f32_e32 v52, 0x3fb8aa3b, v0
	v_exp_f32_e32 v96, v16
	v_fmamk_f32 v16, v0, 0x3c088889, v189
	v_exp_f32_e32 v52, v52
	v_fmaak_f32 v16, v0, v16, 0x3e2aaaab
	v_fma_f32 v16, v0, v16, 0.5
	v_fma_f32 v16, v0, v16, 1.0
	v_mul_f32_e64 v16, v16, -v0
	v_sub_f32_e32 v52, 1.0, v52
	v_cmp_lt_f32_e32 vcc, s4, v0
	s_nop 1
	v_cndmask_b32_e32 v0, v52, v16, vcc
	v_add_f32_e32 v16, 1.0, v1
	v_cmp_gt_f32_e32 vcc, s28, v16
	v_sqrt_f32_e32 v100, v0
	v_add_f32_e32 v0, v17, v53
	v_cndmask_b32_e64 v17, 0, 32, vcc
	v_ldexp_f32 v16, v16, v17
	v_log_f32_e32 v16, v16
	v_mul_f32_e32 v0, 0xbfb8aa3b, v0
	v_exp_f32_e32 v0, v0
	v_mul_f32_e32 v17, 0x3f317217, v16
	v_fma_f32 v17, v16, s0, -v17
	v_fmac_f32_e32 v17, 0x3377d1cf, v16
	v_fmac_f32_e32 v17, 0x3f317217, v16
	v_cmp_lt_f32_e64 s[6:7], |v16|, s1
	v_add_f32_e32 v0, 1.0, v0
	v_rcp_f32_e32 v0, v0
	v_cndmask_b32_e64 v16, v16, v17, s[6:7]
	v_cndmask_b32_e32 v17, 0, v201, vcc
	v_sub_f32_e32 v16, v16, v17
	v_fmamk_f32 v17, v1, 0xbe800000, v188
	v_fma_f32 v17, -v1, v17, 0.5
	v_fma_f32 v17, -v1, v17, 1.0
	v_mul_f32_e32 v17, v1, v17
	v_cmp_gt_f32_e64 s[6:7], s3, v1
	v_cmp_gt_f32_e32 vcc, s2, v97
	v_mul_f32_e32 v0, 0xc1000000, v0
	v_cndmask_b32_e64 v1, v16, v17, s[6:7]
	v_cndmask_b32_e64 v1, v1, -v97, vcc
	v_mul_f32_e32 v0, v0, v1
	v_mul_f32_e32 v1, 0x3fb8aa3b, v0
	v_add_f32_e32 v0, v0, v0
	v_mul_f32_e32 v16, 0x3fb8aa3b, v0
	v_exp_f32_e32 v97, v1
	v_fmamk_f32 v1, v0, 0x3c088889, v189
	v_exp_f32_e32 v16, v16
	v_fmaak_f32 v1, v0, v1, 0x3e2aaaab
	v_fma_f32 v1, v0, v1, 0.5
	v_fma_f32 v1, v0, v1, 1.0
	v_mul_f32_e64 v1, v1, -v0
	v_sub_f32_e32 v16, 1.0, v16
	v_cmp_lt_f32_e32 vcc, s4, v0
	s_nop 1
	v_cndmask_b32_e32 v0, v16, v1, vcc
	v_add_f32_e32 v1, v2, v58
	v_mul_f32_e32 v1, 0xbfb8aa3b, v1
	v_exp_f32_e32 v1, v1
	v_sqrt_f32_e32 v101, v0
	v_add_f32_e32 v0, v18, v54
	v_mul_f32_e32 v0, 0xbfb8aa3b, v0
	v_add_f32_e32 v1, 1.0, v1
	v_rcp_f32_e32 v58, v1
	v_mul_f32_e32 v1, 0xbfb8aa3b, v98
	v_exp_f32_e32 v1, v1
	v_exp_f32_e32 v0, v0
	v_add_f32_e32 v2, 1.0, v1
	v_cmp_gt_f32_e32 vcc, s28, v2
	v_add_f32_e32 v0, 1.0, v0
	v_rcp_f32_e32 v0, v0
	v_cndmask_b32_e64 v16, 0, 32, vcc
	v_ldexp_f32 v2, v2, v16
	v_log_f32_e32 v2, v2
	v_mul_f32_e32 v0, 0xc1000000, v0
	v_mul_f32_e32 v16, 0x3f317217, v2
	v_fma_f32 v16, v2, s0, -v16
	v_fmac_f32_e32 v16, 0x3377d1cf, v2
	v_fmac_f32_e32 v16, 0x3f317217, v2
	v_cmp_lt_f32_e64 s[6:7], |v2|, s1
	s_nop 1
	v_cndmask_b32_e64 v2, v2, v16, s[6:7]
	v_cndmask_b32_e32 v16, 0, v201, vcc
	v_sub_f32_e32 v2, v2, v16
	v_fmamk_f32 v16, v1, 0xbe800000, v188
	v_fma_f32 v16, -v1, v16, 0.5
	v_fma_f32 v16, -v1, v16, 1.0
	v_mul_f32_e32 v16, v1, v16
	v_cmp_gt_f32_e64 s[6:7], s3, v1
	v_cmp_gt_f32_e32 vcc, s2, v98
	s_nop 0
	v_cndmask_b32_e64 v1, v2, v16, s[6:7]
	v_cndmask_b32_e64 v1, v1, -v98, vcc
	v_mul_f32_e32 v0, v0, v1
	v_mul_f32_e32 v1, 0x3fb8aa3b, v0
	v_add_f32_e32 v0, v0, v0
	v_mul_f32_e32 v2, 0x3fb8aa3b, v0
	v_exp_f32_e32 v98, v1
	v_fmamk_f32 v1, v0, 0x3c088889, v189
	v_exp_f32_e32 v2, v2
	v_fmaak_f32 v1, v0, v1, 0x3e2aaaab
	v_fma_f32 v1, v0, v1, 0.5
	v_fma_f32 v1, v0, v1, 1.0
	v_mul_f32_e64 v1, v1, -v0
	v_sub_f32_e32 v2, 1.0, v2
	v_cmp_lt_f32_e32 vcc, s4, v0
	s_nop 1
	v_cndmask_b32_e32 v0, v2, v1, vcc
	v_add_f32_e32 v1, v3, v59
	v_mul_f32_e32 v1, 0xbfb8aa3b, v1
	v_exp_f32_e32 v1, v1
	v_sqrt_f32_e32 v102, v0
	v_add_f32_e32 v0, v19, v55
	v_mul_f32_e32 v0, 0xbfb8aa3b, v0
	v_add_f32_e32 v1, 1.0, v1
	v_rcp_f32_e32 v59, v1
	v_mul_f32_e32 v1, 0xbfb8aa3b, v99
	v_exp_f32_e32 v1, v1
	v_exp_f32_e32 v0, v0
	v_add_f32_e32 v2, 1.0, v1
	v_cmp_gt_f32_e32 vcc, s28, v2
	v_add_f32_e32 v0, 1.0, v0
	v_rcp_f32_e32 v0, v0
	v_cndmask_b32_e64 v3, 0, 32, vcc
	v_ldexp_f32 v2, v2, v3
	v_log_f32_e32 v2, v2
	v_mul_f32_e32 v0, 0xc1000000, v0
	v_mul_f32_e32 v3, 0x3f317217, v2
	v_fma_f32 v3, v2, s0, -v3
	v_fmac_f32_e32 v3, 0x3377d1cf, v2
	v_fmac_f32_e32 v3, 0x3f317217, v2
	v_cmp_lt_f32_e64 s[6:7], |v2|, s1
	s_nop 1
	v_cndmask_b32_e64 v2, v2, v3, s[6:7]
	v_cndmask_b32_e32 v3, 0, v201, vcc
	v_sub_f32_e32 v2, v2, v3
	v_fmamk_f32 v3, v1, 0xbe800000, v188
	v_fma_f32 v3, -v1, v3, 0.5
	v_fma_f32 v3, -v1, v3, 1.0
	v_mul_f32_e32 v3, v1, v3
	v_cmp_gt_f32_e64 s[6:7], s3, v1
	v_cmp_gt_f32_e32 vcc, s2, v99
	s_nop 0
	v_cndmask_b32_e64 v1, v2, v3, s[6:7]
	v_cndmask_b32_e64 v1, v1, -v99, vcc
	v_mul_f32_e32 v0, v0, v1
	v_mul_f32_e32 v1, 0x3fb8aa3b, v0
	v_add_f32_e32 v0, v0, v0
	v_mul_f32_e32 v2, 0x3fb8aa3b, v0
	v_exp_f32_e32 v99, v1
	v_fmamk_f32 v1, v0, 0x3c088889, v189
	v_exp_f32_e32 v2, v2
	v_fmaak_f32 v1, v0, v1, 0x3e2aaaab
	v_fma_f32 v1, v0, v1, 0.5
	v_fma_f32 v1, v0, v1, 1.0
	v_mul_f32_e64 v1, v1, -v0
	v_sub_f32_e32 v2, 1.0, v2
	v_cmp_lt_f32_e32 vcc, s4, v0
	s_nop 1
	v_cndmask_b32_e32 v0, v2, v1, vcc
	v_sqrt_f32_e32 v103, v0
	global_load_dwordx4 v[16:19], v168, s[10:11] offset:160
	global_load_dwordx4 v[0:3], v168, s[12:13] offset:160
	global_load_dwordx4 v[52:55], v168, s[8:9] offset:160
	s_waitcnt vmcnt(2)
	v_add_f32_e32 v16, v20, v16
	v_mul_f32_e32 v16, 0xbfb8aa3b, v16
	v_exp_f32_e32 v16, v16
	s_waitcnt vmcnt(1)
	v_add_f32_e32 v0, v4, v0
	v_mul_f32_e32 v0, 0xbfb8aa3b, v0
	v_exp_f32_e32 v0, v0
	v_add_f32_e32 v16, 1.0, v16
	s_waitcnt vmcnt(0)
	v_mul_f32_e32 v4, 0xbfb8aa3b, v52
	v_rcp_f32_e32 v16, v16
	v_exp_f32_e32 v4, v4
	v_add_f32_e32 v0, 1.0, v0
	v_rcp_f32_e32 v104, v0
	v_mul_f32_e32 v0, 0xc1000000, v16
	v_add_f32_e32 v16, 1.0, v4
	v_cmp_gt_f32_e32 vcc, s28, v16
	v_add_f32_e32 v1, v5, v1
	v_mul_f32_e32 v1, 0xbfb8aa3b, v1
	v_cndmask_b32_e64 v20, 0, 32, vcc
	v_ldexp_f32 v16, v16, v20
	v_log_f32_e32 v16, v16
	v_exp_f32_e32 v1, v1
	v_mul_f32_e32 v20, 0x3f317217, v16
	v_fma_f32 v20, v16, s0, -v20
	v_fmac_f32_e32 v20, 0x3377d1cf, v16
	v_fmac_f32_e32 v20, 0x3f317217, v16
	v_cmp_lt_f32_e64 s[6:7], |v16|, s1
	v_add_f32_e32 v1, 1.0, v1
	v_rcp_f32_e32 v105, v1
	v_cndmask_b32_e64 v16, v16, v20, s[6:7]
	v_cndmask_b32_e32 v20, 0, v201, vcc
	v_sub_f32_e32 v16, v16, v20
	v_fmamk_f32 v20, v4, 0xbe800000, v188
	v_fma_f32 v20, -v4, v20, 0.5
	v_fma_f32 v20, -v4, v20, 1.0
	v_mul_f32_e32 v20, v4, v20
	v_cmp_gt_f32_e64 s[6:7], s3, v4
	v_cmp_gt_f32_e32 vcc, s2, v52
	v_mul_f32_e32 v1, 0xbfb8aa3b, v53
	v_cndmask_b32_e64 v4, v16, v20, s[6:7]
	v_cndmask_b32_e64 v4, v4, -v52, vcc
	v_mul_f32_e32 v0, v0, v4
	v_mul_f32_e32 v4, 0x3fb8aa3b, v0
	v_add_f32_e32 v0, v0, v0
	v_mul_f32_e32 v16, 0x3fb8aa3b, v0
	v_exp_f32_e32 v52, v4
	v_fmamk_f32 v4, v0, 0x3c088889, v189
	v_exp_f32_e32 v16, v16
	v_fmaak_f32 v4, v0, v4, 0x3e2aaaab
	v_exp_f32_e32 v1, v1
	v_fma_f32 v4, v0, v4, 0.5
	v_fma_f32 v4, v0, v4, 1.0
	v_mul_f32_e64 v4, v4, -v0
	v_sub_f32_e32 v16, 1.0, v16
	v_cmp_lt_f32_e32 vcc, s4, v0
	s_nop 1
	v_cndmask_b32_e32 v0, v16, v4, vcc
	v_add_f32_e32 v4, 1.0, v1
	v_cmp_gt_f32_e32 vcc, s28, v4
	v_sqrt_f32_e32 v106, v0
	v_add_f32_e32 v0, v21, v17
	v_cndmask_b32_e64 v5, 0, 32, vcc
	v_ldexp_f32 v4, v4, v5
	v_log_f32_e32 v4, v4
	v_mul_f32_e32 v0, 0xbfb8aa3b, v0
	v_exp_f32_e32 v0, v0
	v_mul_f32_e32 v5, 0x3f317217, v4
	v_fma_f32 v5, v4, s0, -v5
	v_fmac_f32_e32 v5, 0x3377d1cf, v4
	v_fmac_f32_e32 v5, 0x3f317217, v4
	v_cmp_lt_f32_e64 s[6:7], |v4|, s1
	v_add_f32_e32 v0, 1.0, v0
	v_rcp_f32_e32 v0, v0
	v_cndmask_b32_e64 v4, v4, v5, s[6:7]
	v_cndmask_b32_e32 v5, 0, v201, vcc
	v_sub_f32_e32 v4, v4, v5
	v_fmamk_f32 v5, v1, 0xbe800000, v188
	v_fma_f32 v5, -v1, v5, 0.5
	v_fma_f32 v5, -v1, v5, 1.0
	v_mul_f32_e32 v5, v1, v5
	v_cmp_gt_f32_e64 s[6:7], s3, v1
	v_cmp_gt_f32_e32 vcc, s2, v53
	v_mul_f32_e32 v0, 0xc1000000, v0
	v_cndmask_b32_e64 v1, v4, v5, s[6:7]
	v_cndmask_b32_e64 v1, v1, -v53, vcc
	v_mul_f32_e32 v0, v0, v1
	v_mul_f32_e32 v1, 0x3fb8aa3b, v0
	v_add_f32_e32 v0, v0, v0
	v_mul_f32_e32 v4, 0x3fb8aa3b, v0
	v_exp_f32_e32 v53, v1
	v_fmamk_f32 v1, v0, 0x3c088889, v189
	v_exp_f32_e32 v4, v4
	v_fmaak_f32 v1, v0, v1, 0x3e2aaaab
	v_fma_f32 v1, v0, v1, 0.5
	v_fma_f32 v1, v0, v1, 1.0
	v_mul_f32_e64 v1, v1, -v0
	v_sub_f32_e32 v4, 1.0, v4
	v_cmp_lt_f32_e32 vcc, s4, v0
	s_nop 1
	v_cndmask_b32_e32 v0, v4, v1, vcc
	v_add_f32_e32 v1, v6, v2
	v_mul_f32_e32 v1, 0xbfb8aa3b, v1
	v_exp_f32_e32 v1, v1
	v_sqrt_f32_e32 v107, v0
	v_add_f32_e32 v0, v22, v18
	v_mul_f32_e32 v0, 0xbfb8aa3b, v0
	v_add_f32_e32 v1, 1.0, v1
	v_rcp_f32_e32 v108, v1
	v_mul_f32_e32 v1, 0xbfb8aa3b, v54
	v_exp_f32_e32 v1, v1
	v_exp_f32_e32 v0, v0
	v_add_f32_e32 v2, 1.0, v1
	v_cmp_gt_f32_e32 vcc, s28, v2
	v_add_f32_e32 v0, 1.0, v0
	v_rcp_f32_e32 v0, v0
	v_cndmask_b32_e64 v4, 0, 32, vcc
	v_ldexp_f32 v2, v2, v4
	v_log_f32_e32 v2, v2
	v_mul_f32_e32 v0, 0xc1000000, v0
	v_mul_f32_e32 v4, 0x3f317217, v2
	v_fma_f32 v4, v2, s0, -v4
	v_fmac_f32_e32 v4, 0x3377d1cf, v2
	v_fmac_f32_e32 v4, 0x3f317217, v2
	v_cmp_lt_f32_e64 s[6:7], |v2|, s1
	s_nop 1
	v_cndmask_b32_e64 v2, v2, v4, s[6:7]
	v_cndmask_b32_e32 v4, 0, v201, vcc
	v_sub_f32_e32 v2, v2, v4
	v_fmamk_f32 v4, v1, 0xbe800000, v188
	v_fma_f32 v4, -v1, v4, 0.5
	v_fma_f32 v4, -v1, v4, 1.0
	v_mul_f32_e32 v4, v1, v4
	v_cmp_gt_f32_e64 s[6:7], s3, v1
	v_cmp_gt_f32_e32 vcc, s2, v54
	s_nop 0
	v_cndmask_b32_e64 v1, v2, v4, s[6:7]
	v_cndmask_b32_e64 v1, v1, -v54, vcc
	v_mul_f32_e32 v0, v0, v1
	v_mul_f32_e32 v1, 0x3fb8aa3b, v0
	v_add_f32_e32 v0, v0, v0
	v_mul_f32_e32 v2, 0x3fb8aa3b, v0
	v_exp_f32_e32 v54, v1
	v_fmamk_f32 v1, v0, 0x3c088889, v189
	v_exp_f32_e32 v2, v2
	v_fmaak_f32 v1, v0, v1, 0x3e2aaaab
	v_fma_f32 v1, v0, v1, 0.5
	v_fma_f32 v1, v0, v1, 1.0
	v_mul_f32_e64 v1, v1, -v0
	v_sub_f32_e32 v2, 1.0, v2
	v_cmp_lt_f32_e32 vcc, s4, v0
	s_nop 1
	v_cndmask_b32_e32 v0, v2, v1, vcc
	v_sqrt_f32_e32 v110, v0
	v_add_f32_e32 v0, v23, v19
	v_add_f32_e32 v1, v7, v3
	global_load_dwordx4 v[4:7], v168, s[10:11] offset:192
	global_load_dwordx4 v[16:19], v168, s[12:13] offset:192
	global_load_dwordx4 v[20:23], v168, s[8:9] offset:192
	v_mul_f32_e32 v1, 0xbfb8aa3b, v1
	v_exp_f32_e32 v1, v1
	v_mul_f32_e32 v0, 0xbfb8aa3b, v0
	v_exp_f32_e32 v0, v0
	v_add_f32_e32 v1, 1.0, v1
	v_rcp_f32_e32 v109, v1
	v_mul_f32_e32 v1, 0xbfb8aa3b, v55
	v_exp_f32_e32 v1, v1
	v_add_f32_e32 v0, 1.0, v0
	v_rcp_f32_e32 v0, v0
	v_add_f32_e32 v2, 1.0, v1
	v_cmp_gt_f32_e32 vcc, s28, v2
	v_mul_f32_e32 v0, 0xc1000000, v0
	s_waitcnt vmcnt(2)
	v_add_f32_e32 v4, v24, v4
	v_cndmask_b32_e64 v3, 0, 32, vcc
	v_ldexp_f32 v2, v2, v3
	v_log_f32_e32 v2, v2
	s_waitcnt vmcnt(1)
	v_add_f32_e32 v8, v8, v16
	v_mul_f32_e32 v8, 0xbfb8aa3b, v8
	v_exp_f32_e32 v8, v8
	v_mul_f32_e32 v3, 0x3f317217, v2
	v_fma_f32 v3, v2, s0, -v3
	v_fmac_f32_e32 v3, 0x3377d1cf, v2
	v_fmac_f32_e32 v3, 0x3f317217, v2
	v_cmp_lt_f32_e64 s[6:7], |v2|, s1
	v_add_f32_e32 v8, 1.0, v8
	v_rcp_f32_e32 v112, v8
	v_cndmask_b32_e64 v2, v2, v3, s[6:7]
	v_cndmask_b32_e32 v3, 0, v201, vcc
	v_sub_f32_e32 v2, v2, v3
	v_fmamk_f32 v3, v1, 0xbe800000, v188
	v_fma_f32 v3, -v1, v3, 0.5
	v_fma_f32 v3, -v1, v3, 1.0
	v_mul_f32_e32 v3, v1, v3
	v_cmp_gt_f32_e64 s[6:7], s3, v1
	v_cmp_gt_f32_e32 vcc, s2, v55
	s_waitcnt vmcnt(0)
	v_mul_f32_e32 v8, 0xbfb8aa3b, v20
	v_cndmask_b32_e64 v1, v2, v3, s[6:7]
	v_cndmask_b32_e64 v1, v1, -v55, vcc
	v_mul_f32_e32 v0, v0, v1
	v_mul_f32_e32 v1, 0x3fb8aa3b, v0
	v_add_f32_e32 v0, v0, v0
	v_mul_f32_e32 v2, 0x3fb8aa3b, v0
	v_exp_f32_e32 v55, v1
	v_fmamk_f32 v1, v0, 0x3c088889, v189
	v_exp_f32_e32 v2, v2
	v_exp_f32_e32 v8, v8
	v_fmaak_f32 v1, v0, v1, 0x3e2aaaab
	v_fma_f32 v1, v0, v1, 0.5
	v_fma_f32 v1, v0, v1, 1.0
	v_mul_f32_e64 v1, v1, -v0
	v_sub_f32_e32 v2, 1.0, v2
	v_cmp_lt_f32_e32 vcc, s4, v0
	v_add_f32_e32 v16, 1.0, v8
	v_mul_f32_e32 v4, 0xbfb8aa3b, v4
	v_cndmask_b32_e32 v0, v2, v1, vcc
	v_cmp_gt_f32_e32 vcc, s28, v16
	v_exp_f32_e32 v4, v4
	v_sqrt_f32_e32 v111, v0
	v_cndmask_b32_e64 v24, 0, 32, vcc
	v_ldexp_f32 v16, v16, v24
	v_log_f32_e32 v16, v16
	v_add_f32_e32 v4, 1.0, v4
	v_rcp_f32_e32 v4, v4
	ds_read_b128 v[0:3], v124 offset:192
	v_mul_f32_e32 v24, 0x3f317217, v16
	v_fma_f32 v24, v16, s0, -v24
	v_fmac_f32_e32 v24, 0x3377d1cf, v16
	v_fmac_f32_e32 v24, 0x3f317217, v16
	v_cmp_lt_f32_e64 s[6:7], |v16|, s1
	v_mul_f32_e32 v4, 0xc1000000, v4
	s_nop 0
	v_cndmask_b32_e64 v16, v16, v24, s[6:7]
	v_cndmask_b32_e32 v24, 0, v201, vcc
	v_sub_f32_e32 v16, v16, v24
	v_fmamk_f32 v24, v8, 0xbe800000, v188
	v_fma_f32 v24, -v8, v24, 0.5
	v_fma_f32 v24, -v8, v24, 1.0
	v_mul_f32_e32 v24, v8, v24
	v_cmp_gt_f32_e64 s[6:7], s3, v8
	v_cmp_gt_f32_e32 vcc, s2, v20
	s_nop 0
	v_cndmask_b32_e64 v8, v16, v24, s[6:7]
	v_cndmask_b32_e64 v8, v8, -v20, vcc
	v_mul_f32_e32 v4, v4, v8
	v_mul_f32_e32 v8, 0x3fb8aa3b, v4
	v_add_f32_e32 v4, v4, v4
	v_mul_f32_e32 v16, 0x3fb8aa3b, v4
	v_exp_f32_e32 v116, v8
	v_fmamk_f32 v8, v4, 0x3c088889, v189
	v_exp_f32_e32 v16, v16
	v_fmaak_f32 v8, v4, v8, 0x3e2aaaab
	v_fma_f32 v8, v4, v8, 0.5
	v_fma_f32 v8, v4, v8, 1.0
	v_mul_f32_e64 v8, v8, -v4
	v_sub_f32_e32 v16, 1.0, v16
	v_cmp_lt_f32_e32 vcc, s4, v4
	s_nop 1
	v_cndmask_b32_e32 v4, v16, v8, vcc
	v_sqrt_f32_e32 v120, v4
	v_add_f32_e32 v4, v25, v5
	v_add_f32_e32 v5, v9, v17
	v_mul_f32_e32 v5, 0xbfb8aa3b, v5
	v_exp_f32_e32 v5, v5
	v_mul_f32_e32 v4, 0xbfb8aa3b, v4
	v_exp_f32_e32 v4, v4
	v_add_f32_e32 v5, 1.0, v5
	v_rcp_f32_e32 v113, v5
	v_mul_f32_e32 v5, 0xbfb8aa3b, v21
	v_exp_f32_e32 v5, v5
	v_add_f32_e32 v4, 1.0, v4
	v_rcp_f32_e32 v4, v4
	v_add_f32_e32 v8, 1.0, v5
	v_cmp_gt_f32_e32 vcc, s28, v8
	v_mul_f32_e32 v4, 0xc1000000, v4
	s_nop 0
	v_cndmask_b32_e64 v9, 0, 32, vcc
	v_ldexp_f32 v8, v8, v9
	v_log_f32_e32 v8, v8
	s_nop 0
	v_mul_f32_e32 v9, 0x3f317217, v8
	v_fma_f32 v9, v8, s0, -v9
	v_fmac_f32_e32 v9, 0x3377d1cf, v8
	v_fmac_f32_e32 v9, 0x3f317217, v8
	v_cmp_lt_f32_e64 s[6:7], |v8|, s1
	s_nop 1
	v_cndmask_b32_e64 v8, v8, v9, s[6:7]
	v_cndmask_b32_e32 v9, 0, v201, vcc
	v_sub_f32_e32 v8, v8, v9
	v_fmamk_f32 v9, v5, 0xbe800000, v188
	v_fma_f32 v9, -v5, v9, 0.5
	v_fma_f32 v9, -v5, v9, 1.0
	v_mul_f32_e32 v9, v5, v9
	v_cmp_gt_f32_e64 s[6:7], s3, v5
	v_cmp_gt_f32_e32 vcc, s2, v21
	s_nop 0
	v_cndmask_b32_e64 v5, v8, v9, s[6:7]
	v_cndmask_b32_e64 v5, v5, -v21, vcc
	v_mul_f32_e32 v4, v4, v5
	v_mul_f32_e32 v5, 0x3fb8aa3b, v4
	v_add_f32_e32 v4, v4, v4
	v_mul_f32_e32 v8, 0x3fb8aa3b, v4
	v_exp_f32_e32 v117, v5
	v_fmamk_f32 v5, v4, 0x3c088889, v189
	v_exp_f32_e32 v8, v8
	v_fmaak_f32 v5, v4, v5, 0x3e2aaaab
	v_fma_f32 v5, v4, v5, 0.5
	v_fma_f32 v5, v4, v5, 1.0
	v_mul_f32_e64 v5, v5, -v4
	v_sub_f32_e32 v8, 1.0, v8
	v_cmp_lt_f32_e32 vcc, s4, v4
	s_nop 1
	v_cndmask_b32_e32 v4, v8, v5, vcc
	v_add_f32_e32 v5, v10, v18
	v_mul_f32_e32 v5, 0xbfb8aa3b, v5
	v_exp_f32_e32 v5, v5
	v_sqrt_f32_e32 v121, v4
	v_add_f32_e32 v4, v26, v6
	v_mul_f32_e32 v4, 0xbfb8aa3b, v4
	v_add_f32_e32 v5, 1.0, v5
	v_rcp_f32_e32 v114, v5
	v_mul_f32_e32 v5, 0xbfb8aa3b, v22
	v_exp_f32_e32 v5, v5
	v_exp_f32_e32 v4, v4
	v_add_f32_e32 v6, 1.0, v5
	v_cmp_gt_f32_e32 vcc, s28, v6
	v_add_f32_e32 v4, 1.0, v4
	v_rcp_f32_e32 v4, v4
	v_cndmask_b32_e64 v8, 0, 32, vcc
	v_ldexp_f32 v6, v6, v8
	v_log_f32_e32 v6, v6
	v_mul_f32_e32 v4, 0xc1000000, v4
	v_mul_f32_e32 v8, 0x3f317217, v6
	v_fma_f32 v8, v6, s0, -v8
	v_fmac_f32_e32 v8, 0x3377d1cf, v6
	v_fmac_f32_e32 v8, 0x3f317217, v6
	v_cmp_lt_f32_e64 s[6:7], |v6|, s1
	s_nop 1
	v_cndmask_b32_e64 v6, v6, v8, s[6:7]
	v_cndmask_b32_e32 v8, 0, v201, vcc
	v_sub_f32_e32 v6, v6, v8
	v_fmamk_f32 v8, v5, 0xbe800000, v188
	v_fma_f32 v8, -v5, v8, 0.5
	v_fma_f32 v8, -v5, v8, 1.0
	v_mul_f32_e32 v8, v5, v8
	v_cmp_gt_f32_e64 s[6:7], s3, v5
	v_cmp_gt_f32_e32 vcc, s2, v22
	s_nop 0
	v_cndmask_b32_e64 v5, v6, v8, s[6:7]
	v_cndmask_b32_e64 v5, v5, -v22, vcc
	v_mul_f32_e32 v4, v4, v5
	v_mul_f32_e32 v5, 0x3fb8aa3b, v4
	v_add_f32_e32 v4, v4, v4
	v_mul_f32_e32 v6, 0x3fb8aa3b, v4
	v_exp_f32_e32 v118, v5
	v_fmamk_f32 v5, v4, 0x3c088889, v189
	v_exp_f32_e32 v6, v6
	v_fmaak_f32 v5, v4, v5, 0x3e2aaaab
	v_fma_f32 v5, v4, v5, 0.5
	v_fma_f32 v5, v4, v5, 1.0
	v_mul_f32_e64 v5, v5, -v4
	v_sub_f32_e32 v6, 1.0, v6
	v_cmp_lt_f32_e32 vcc, s4, v4
	s_nop 1
	v_cndmask_b32_e32 v4, v6, v5, vcc
	v_add_f32_e32 v5, v11, v19
	v_mul_f32_e32 v5, 0xbfb8aa3b, v5
	v_exp_f32_e32 v5, v5
	v_sqrt_f32_e32 v122, v4
	v_add_f32_e32 v4, v27, v7
	v_mul_f32_e32 v4, 0xbfb8aa3b, v4
	v_add_f32_e32 v5, 1.0, v5
	v_rcp_f32_e32 v115, v5
	v_mul_f32_e32 v5, 0xbfb8aa3b, v23
	v_exp_f32_e32 v5, v5
	v_exp_f32_e32 v4, v4
	v_add_f32_e32 v6, 1.0, v5
	v_cmp_gt_f32_e32 vcc, s28, v6
	v_add_f32_e32 v4, 1.0, v4
	v_rcp_f32_e32 v4, v4
	v_cndmask_b32_e64 v7, 0, 32, vcc
	v_ldexp_f32 v6, v6, v7
	v_log_f32_e32 v6, v6
	v_mul_f32_e32 v4, 0xc1000000, v4
	v_mul_f32_e32 v7, 0x3f317217, v6
	v_fma_f32 v7, v6, s0, -v7
	v_fmac_f32_e32 v7, 0x3377d1cf, v6
	v_fmac_f32_e32 v7, 0x3f317217, v6
	v_cmp_lt_f32_e64 s[6:7], |v6|, s1
	s_nop 1
	v_cndmask_b32_e64 v6, v6, v7, s[6:7]
	v_cndmask_b32_e32 v7, 0, v201, vcc
	v_sub_f32_e32 v6, v6, v7
	v_fmamk_f32 v7, v5, 0xbe800000, v188
	v_fma_f32 v7, -v5, v7, 0.5
	v_fma_f32 v7, -v5, v7, 1.0
	v_mul_f32_e32 v7, v5, v7
	v_cmp_gt_f32_e64 s[6:7], s3, v5
	v_cmp_gt_f32_e32 vcc, s2, v23
	s_nop 0
	v_cndmask_b32_e64 v5, v6, v7, s[6:7]
	v_cndmask_b32_e64 v5, v5, -v23, vcc
	global_load_dwordx4 v[20:23], v168, s[10:11] offset:224
	global_load_dwordx4 v[16:19], v168, s[12:13] offset:224
	global_load_dwordx4 v[8:11], v168, s[8:9] offset:224
	v_mul_f32_e32 v4, v4, v5
	v_mul_f32_e32 v5, 0x3fb8aa3b, v4
	v_add_f32_e32 v4, v4, v4
	v_mul_f32_e32 v6, 0x3fb8aa3b, v4
	v_exp_f32_e32 v119, v5
	v_fmamk_f32 v5, v4, 0x3c088889, v189
	v_exp_f32_e32 v6, v6
	v_fmaak_f32 v5, v4, v5, 0x3e2aaaab
	v_fma_f32 v5, v4, v5, 0.5
	v_fma_f32 v5, v4, v5, 1.0
	v_mul_f32_e64 v5, v5, -v4
	v_sub_f32_e32 v6, 1.0, v6
	v_cmp_lt_f32_e32 vcc, s4, v4
	s_waitcnt vmcnt(2)
	v_add_f32_e32 v20, v28, v20
	v_mul_f32_e32 v20, 0xbfb8aa3b, v20
	v_exp_f32_e32 v20, v20
	s_waitcnt vmcnt(1)
	v_add_f32_e32 v12, v12, v16
	v_mul_f32_e32 v12, 0xbfb8aa3b, v12
	v_exp_f32_e32 v12, v12
	v_add_f32_e32 v20, 1.0, v20
	s_waitcnt vmcnt(0)
	v_mul_f32_e32 v16, 0xbfb8aa3b, v8
	v_rcp_f32_e32 v20, v20
	v_exp_f32_e32 v16, v16
	v_cndmask_b32_e32 v4, v6, v5, vcc
	v_add_f32_e32 v12, 1.0, v12
	v_sqrt_f32_e32 v123, v4
	ds_read_b128 v[4:7], v124 offset:224
	v_rcp_f32_e32 v124, v12
	v_mul_f32_e32 v12, 0xc1000000, v20
	v_add_f32_e32 v20, 1.0, v16
	v_cmp_gt_f32_e32 vcc, s28, v20
	s_nop 1
	v_cndmask_b32_e64 v24, 0, 32, vcc
	v_ldexp_f32 v20, v20, v24
	v_log_f32_e32 v20, v20
	s_nop 0
	v_mul_f32_e32 v24, 0x3f317217, v20
	v_fma_f32 v24, v20, s0, -v24
	v_fmac_f32_e32 v24, 0x3377d1cf, v20
	v_fmac_f32_e32 v24, 0x3f317217, v20
	v_cmp_lt_f32_e64 s[6:7], |v20|, s1
	s_nop 1
	v_cndmask_b32_e64 v20, v20, v24, s[6:7]
	v_cndmask_b32_e32 v24, 0, v201, vcc
	v_sub_f32_e32 v20, v20, v24
	v_fmamk_f32 v24, v16, 0xbe800000, v188
	v_fma_f32 v24, -v16, v24, 0.5
	v_fma_f32 v24, -v16, v24, 1.0
	v_mul_f32_e32 v24, v16, v24
	v_cmp_gt_f32_e64 s[6:7], s3, v16
	v_cmp_gt_f32_e32 vcc, s2, v8
	s_nop 0
	v_cndmask_b32_e64 v16, v20, v24, s[6:7]
	v_cndmask_b32_e64 v8, v16, -v8, vcc
	v_mul_f32_e32 v8, v12, v8
	v_mul_f32_e32 v12, 0x3fb8aa3b, v8
	v_add_f32_e32 v8, v8, v8
	v_mul_f32_e32 v16, 0x3fb8aa3b, v8
	v_exp_f32_e32 v126, v12
	v_fmamk_f32 v12, v8, 0x3c088889, v189
	v_exp_f32_e32 v16, v16
	v_fmaak_f32 v12, v8, v12, 0x3e2aaaab
	v_fma_f32 v12, v8, v12, 0.5
	v_fma_f32 v12, v8, v12, 1.0
	v_mul_f32_e64 v12, v12, -v8
	v_sub_f32_e32 v16, 1.0, v16
	v_cmp_lt_f32_e32 vcc, s4, v8
	s_nop 1
	v_cndmask_b32_e32 v8, v16, v12, vcc
	v_add_f32_e32 v12, v13, v17
	v_mul_f32_e32 v12, 0xbfb8aa3b, v12
	v_exp_f32_e32 v12, v12
	v_sqrt_f32_e32 v128, v8
	v_add_f32_e32 v8, v29, v21
	v_mul_f32_e32 v8, 0xbfb8aa3b, v8
	v_add_f32_e32 v12, 1.0, v12
	v_rcp_f32_e32 v125, v12
	v_mul_f32_e32 v12, 0xbfb8aa3b, v9
	v_exp_f32_e32 v12, v12
	v_exp_f32_e32 v8, v8
	v_add_f32_e32 v13, 1.0, v12
	v_cmp_gt_f32_e32 vcc, s28, v13
	v_add_f32_e32 v8, 1.0, v8
	v_rcp_f32_e32 v8, v8
	v_cndmask_b32_e64 v16, 0, 32, vcc
	v_ldexp_f32 v13, v13, v16
	v_log_f32_e32 v13, v13
	v_mul_f32_e32 v8, 0xc1000000, v8
	v_mul_f32_e32 v16, 0x3f317217, v13
	v_fma_f32 v16, v13, s0, -v16
	v_fmac_f32_e32 v16, 0x3377d1cf, v13
	v_fmac_f32_e32 v16, 0x3f317217, v13
	v_cmp_lt_f32_e64 s[6:7], |v13|, s1
	s_nop 1
	v_cndmask_b32_e64 v13, v13, v16, s[6:7]
	v_cndmask_b32_e32 v16, 0, v201, vcc
	v_sub_f32_e32 v13, v13, v16
	v_fmamk_f32 v16, v12, 0xbe800000, v188
	v_fma_f32 v16, -v12, v16, 0.5
	v_fma_f32 v16, -v12, v16, 1.0
	v_mul_f32_e32 v16, v12, v16
	v_cmp_gt_f32_e64 s[6:7], s3, v12
	v_cmp_gt_f32_e32 vcc, s2, v9
	s_nop 0
	v_cndmask_b32_e64 v12, v13, v16, s[6:7]
	v_cndmask_b32_e64 v9, v12, -v9, vcc
	v_mul_f32_e32 v8, v8, v9
	v_mul_f32_e32 v9, 0x3fb8aa3b, v8
	v_add_f32_e32 v8, v8, v8
	v_mul_f32_e32 v12, 0x3fb8aa3b, v8
	v_exp_f32_e32 v127, v9
	v_fmamk_f32 v9, v8, 0x3c088889, v189
	v_exp_f32_e32 v12, v12
	v_fmaak_f32 v9, v8, v9, 0x3e2aaaab
	v_fma_f32 v9, v8, v9, 0.5
	v_fma_f32 v9, v8, v9, 1.0
	v_mul_f32_e64 v9, v9, -v8
	v_sub_f32_e32 v12, 1.0, v12
	v_cmp_lt_f32_e32 vcc, s4, v8
	s_nop 1
	v_cndmask_b32_e32 v8, v12, v9, vcc
	v_add_f32_e32 v9, v14, v18
	v_mul_f32_e32 v9, 0xbfb8aa3b, v9
	v_exp_f32_e32 v9, v9
	v_sqrt_f32_e32 v129, v8
	v_add_f32_e32 v8, v30, v22
	v_mul_f32_e32 v8, 0xbfb8aa3b, v8
	v_add_f32_e32 v9, 1.0, v9
	v_rcp_f32_e32 v130, v9
	v_mul_f32_e32 v9, 0xbfb8aa3b, v10
	v_exp_f32_e32 v9, v9
	v_exp_f32_e32 v8, v8
	v_add_f32_e32 v12, 1.0, v9
	v_cmp_gt_f32_e32 vcc, s28, v12
	v_add_f32_e32 v8, 1.0, v8
	v_rcp_f32_e32 v8, v8
	v_cndmask_b32_e64 v13, 0, 32, vcc
	v_ldexp_f32 v12, v12, v13
	v_log_f32_e32 v12, v12
	v_mul_f32_e32 v8, 0xc1000000, v8
	v_mul_f32_e32 v13, 0x3f317217, v12
	v_fma_f32 v13, v12, s0, -v13
	v_fmac_f32_e32 v13, 0x3377d1cf, v12
	v_fmac_f32_e32 v13, 0x3f317217, v12
	v_cmp_lt_f32_e64 s[6:7], |v12|, s1
	s_nop 1
	v_cndmask_b32_e64 v12, v12, v13, s[6:7]
	v_cndmask_b32_e32 v13, 0, v201, vcc
	v_sub_f32_e32 v12, v12, v13
	v_fmamk_f32 v13, v9, 0xbe800000, v188
	v_fma_f32 v13, -v9, v13, 0.5
	v_fma_f32 v13, -v9, v13, 1.0
	v_mul_f32_e32 v13, v9, v13
	v_cmp_gt_f32_e64 s[6:7], s3, v9
	v_cmp_gt_f32_e32 vcc, s2, v10
	s_nop 0
	v_cndmask_b32_e64 v9, v12, v13, s[6:7]
	v_cndmask_b32_e64 v9, v9, -v10, vcc
	v_mul_f32_e32 v8, v8, v9
	v_mul_f32_e32 v9, 0x3fb8aa3b, v8
	v_add_f32_e32 v8, v8, v8
	v_mul_f32_e32 v10, 0x3fb8aa3b, v8
	v_exp_f32_e32 v132, v9
	v_fmamk_f32 v9, v8, 0x3c088889, v189
	v_exp_f32_e32 v10, v10
	v_fmaak_f32 v9, v8, v9, 0x3e2aaaab
	v_fma_f32 v9, v8, v9, 0.5
	v_fma_f32 v9, v8, v9, 1.0
	v_mul_f32_e64 v9, v9, -v8
	v_sub_f32_e32 v10, 1.0, v10
	v_cmp_lt_f32_e32 vcc, s4, v8
	s_nop 1
	v_cndmask_b32_e32 v8, v10, v9, vcc
	v_add_f32_e32 v9, v15, v19
	v_mul_f32_e32 v9, 0xbfb8aa3b, v9
	v_exp_f32_e32 v9, v9
	v_sqrt_f32_e32 v134, v8
	v_add_f32_e32 v8, v31, v23
	v_mul_f32_e32 v8, 0xbfb8aa3b, v8
	v_add_f32_e32 v9, 1.0, v9
	v_rcp_f32_e32 v131, v9
	v_mul_f32_e32 v9, 0xbfb8aa3b, v11
	v_exp_f32_e32 v9, v9
	v_exp_f32_e32 v8, v8
	v_add_f32_e32 v10, 1.0, v9
	v_cmp_gt_f32_e32 vcc, s28, v10
	v_add_f32_e32 v8, 1.0, v8
	v_rcp_f32_e32 v8, v8
	v_cndmask_b32_e64 v12, 0, 32, vcc
	v_ldexp_f32 v10, v10, v12
	v_log_f32_e32 v10, v10
	v_mul_f32_e32 v8, 0xc1000000, v8
	v_mul_f32_e32 v12, 0x3f317217, v10
	v_fma_f32 v12, v10, s0, -v12
	v_fmac_f32_e32 v12, 0x3377d1cf, v10
	v_fmac_f32_e32 v12, 0x3f317217, v10
	v_cmp_lt_f32_e64 s[6:7], |v10|, s1
	s_nop 1
	v_cndmask_b32_e64 v10, v10, v12, s[6:7]
	v_cndmask_b32_e32 v12, 0, v201, vcc
	v_sub_f32_e32 v10, v10, v12
	v_fmamk_f32 v12, v9, 0xbe800000, v188
	v_fma_f32 v12, -v9, v12, 0.5
	v_fma_f32 v12, -v9, v12, 1.0
	v_mul_f32_e32 v12, v9, v12
	v_cmp_gt_f32_e64 s[6:7], s3, v9
	v_cmp_gt_f32_e32 vcc, s2, v11
	s_nop 0
	v_cndmask_b32_e64 v9, v10, v12, s[6:7]
	v_cndmask_b32_e64 v9, v9, -v11, vcc
	v_mul_f32_e32 v8, v8, v9
	v_mul_f32_e32 v9, 0x3fb8aa3b, v8
	v_add_f32_e32 v8, v8, v8
	v_mul_f32_e32 v10, 0x3fb8aa3b, v8
	v_exp_f32_e32 v133, v9
	v_fmamk_f32 v9, v8, 0x3c088889, v189
	v_exp_f32_e32 v10, v10
	v_fmaak_f32 v9, v8, v9, 0x3e2aaaab
	v_fma_f32 v9, v8, v9, 0.5
	v_fma_f32 v9, v8, v9, 1.0
	v_mul_f32_e64 v9, v9, -v8
	v_sub_f32_e32 v10, 1.0, v10
	v_cmp_lt_f32_e32 vcc, s4, v8
	s_nop 1
	v_cndmask_b32_e32 v8, v10, v9, vcc
	v_sqrt_f32_e32 v135, v8
	v_and_b32_e32 v8, 0x60, v191
	v_add_u32_e32 v9, -1, v191
	v_cmp_lt_i32_e32 vcc, v9, v8
	s_nop 1
	v_cndmask_b32_e32 v9, v9, v191, vcc
	v_and_b32_e32 v165, 15, v162
	v_mov_b32_dpp v10, v137 row_shr:1 row_mask:0xf bank_mask:0xf
	v_cmp_eq_u32_e32 vcc, 0, v165
	v_mov_b32_dpp v11, v139 row_shr:1 row_mask:0xf bank_mask:0xf
	v_mov_b32_dpp v9, v136 row_shr:1 row_mask:0xf bank_mask:0xf
	v_mov_b32_dpp v14, v68 row_shr:1 row_mask:0xf bank_mask:0xf
	s_waitcnt lgkmcnt(3)
	v_fma_f32 v10, v136, v10, v137
	v_cndmask_b32_e32 v12, v10, v137, vcc
	v_mov_b32_dpp v10, v138 row_shr:1 row_mask:0xf bank_mask:0xf
	s_waitcnt lgkmcnt(3)
	v_fma_f32 v11, v138, v11, v139
	v_cndmask_b32_e32 v16, v11, v139, vcc
	v_mov_b32_dpp v11, v141 row_shr:1 row_mask:0xf bank_mask:0xf
	v_mov_b32_dpp v15, v69 row_shr:1 row_mask:0xf bank_mask:0xf
	s_waitcnt lgkmcnt(2)
	v_mul_f32_e32 v10, v138, v10
	v_cndmask_b32_e32 v13, v10, v138, vcc
	v_mov_b32_dpp v10, v140 row_shr:1 row_mask:0xf bank_mask:0xf
	s_waitcnt lgkmcnt(2)
	v_fma_f32 v11, v140, v11, v141
	v_cndmask_b32_e32 v18, v11, v141, vcc
	v_mov_b32_dpp v11, v143 row_shr:1 row_mask:0xf bank_mask:0xf
	v_mul_f32_e32 v9, v136, v9
	s_waitcnt lgkmcnt(1)
	v_mul_f32_e32 v10, v140, v10
	v_cndmask_b32_e32 v17, v10, v140, vcc
	v_mov_b32_dpp v10, v142 row_shr:1 row_mask:0xf bank_mask:0xf
	s_waitcnt lgkmcnt(1)
	v_fma_f32 v11, v142, v11, v143
	v_cndmask_b32_e32 v20, v11, v143, vcc
	v_mov_b32_dpp v11, v63 row_shr:1 row_mask:0xf bank_mask:0xf
	v_cndmask_b32_e32 v9, v9, v136, vcc
	s_waitcnt lgkmcnt(1)
	v_mul_f32_e32 v10, v142, v10
	v_cndmask_b32_e32 v19, v10, v142, vcc
	v_mov_b32_dpp v10, v62 row_shr:1 row_mask:0xf bank_mask:0xf
	v_mov_b32_dpp v28, v76 row_shr:1 row_mask:0xf bank_mask:0xf
	v_mov_b32_dpp v29, v77 row_shr:1 row_mask:0xf bank_mask:0xf
	v_mov_b32_dpp v24, v78 row_shr:1 row_mask:0xf bank_mask:0xf
	v_mov_b32_dpp v25, v79 row_shr:1 row_mask:0xf bank_mask:0xf
	v_mov_b32_dpp v30, v86 row_shr:1 row_mask:0xf bank_mask:0xf
	v_mov_b32_dpp v31, v87 row_shr:1 row_mask:0xf bank_mask:0xf
	v_mov_b32_dpp v26, v92 row_shr:1 row_mask:0xf bank_mask:0xf
	v_mov_b32_dpp v27, v93 row_shr:1 row_mask:0xf bank_mask:0xf
	v_mov_b32_dpp v158, v96 row_shr:1 row_mask:0xf bank_mask:0xf
	v_mov_b32_dpp v159, v97 row_shr:1 row_mask:0xf bank_mask:0xf
	v_mov_b32_dpp v156, v98 row_shr:1 row_mask:0xf bank_mask:0xf
	v_mov_b32_dpp v157, v99 row_shr:1 row_mask:0xf bank_mask:0xf
	v_mov_b32_dpp v154, v52 row_shr:1 row_mask:0xf bank_mask:0xf
	v_mov_b32_dpp v155, v53 row_shr:1 row_mask:0xf bank_mask:0xf
	v_mov_b32_dpp v152, v54 row_shr:1 row_mask:0xf bank_mask:0xf
	v_mov_b32_dpp v153, v55 row_shr:1 row_mask:0xf bank_mask:0xf
	v_mov_b32_dpp v150, v116 row_shr:1 row_mask:0xf bank_mask:0xf
	v_mov_b32_dpp v151, v117 row_shr:1 row_mask:0xf bank_mask:0xf
	v_mov_b32_dpp v148, v118 row_shr:1 row_mask:0xf bank_mask:0xf
	v_mov_b32_dpp v149, v119 row_shr:1 row_mask:0xf bank_mask:0xf
	v_mov_b32_dpp v146, v126 row_shr:1 row_mask:0xf bank_mask:0xf
	v_mov_b32_dpp v147, v127 row_shr:1 row_mask:0xf bank_mask:0xf
	v_mov_b32_dpp v136, v132 row_shr:1 row_mask:0xf bank_mask:0xf
	v_mov_b32_dpp v137, v133 row_shr:1 row_mask:0xf bank_mask:0xf
	v_add_u32_e32 v21, -2, v191
	v_cmp_lt_i32_e64 s[6:7], v21, v8
	s_nop 1
	v_cndmask_b32_e64 v21, v21, v191, s[6:7]
	v_lshlrev_b32_e32 v166, 2, v21
	v_mov_b32_dpp v21, v9 row_shr:2 row_mask:0xf bank_mask:0xf
	v_mov_b32_dpp v22, v12 row_shr:2 row_mask:0xf bank_mask:0xf
	v_cmp_gt_u32_e64 s[6:7], 2, v165
	s_waitcnt lgkmcnt(1)
	v_mul_f32_e32 v21, v9, v21
	s_waitcnt lgkmcnt(0)
	v_fma_f32 v22, v9, v22, v12
	v_cndmask_b32_e64 v9, v21, v9, s[6:7]
	v_cndmask_b32_e64 v12, v22, v12, s[6:7]
	v_mov_b32_dpp v21, v13 row_shr:2 row_mask:0xf bank_mask:0xf
	v_mov_b32_dpp v22, v16 row_shr:2 row_mask:0xf bank_mask:0xf
	s_waitcnt lgkmcnt(1)
	v_mul_f32_e32 v21, v13, v21
	s_waitcnt lgkmcnt(0)
	v_fma_f32 v22, v13, v22, v16
	v_cndmask_b32_e64 v13, v21, v13, s[6:7]
	v_cndmask_b32_e64 v16, v22, v16, s[6:7]
	v_mov_b32_dpp v21, v17 row_shr:2 row_mask:0xf bank_mask:0xf
	v_mov_b32_dpp v22, v18 row_shr:2 row_mask:0xf bank_mask:0xf
	s_waitcnt lgkmcnt(1)
	v_mul_f32_e32 v21, v17, v21
	s_waitcnt lgkmcnt(0)
	v_fma_f32 v22, v17, v22, v18
	v_cndmask_b32_e64 v17, v21, v17, s[6:7]
	v_cndmask_b32_e64 v18, v22, v18, s[6:7]
	v_mov_b32_dpp v21, v19 row_shr:2 row_mask:0xf bank_mask:0xf
	v_mov_b32_dpp v22, v20 row_shr:2 row_mask:0xf bank_mask:0xf
	s_waitcnt lgkmcnt(1)
	v_mul_f32_e32 v21, v19, v21
	s_waitcnt lgkmcnt(0)
	v_fma_f32 v22, v19, v22, v20
	v_cndmask_b32_e64 v19, v21, v19, s[6:7]
	v_cndmask_b32_e64 v20, v22, v20, s[6:7]
	v_add_u32_e32 v21, -4, v191
	v_cmp_lt_i32_e64 s[8:9], v21, v8
	s_nop 1
	v_cndmask_b32_e64 v21, v21, v191, s[8:9]
	v_lshlrev_b32_e32 v167, 2, v21
	v_mov_b32_dpp v21, v9 row_shr:4 row_mask:0xf bank_mask:0xf
	v_mov_b32_dpp v22, v12 row_shr:4 row_mask:0xf bank_mask:0xf
	v_cmp_gt_u32_e64 s[8:9], 4, v165
	s_waitcnt lgkmcnt(1)
	v_mul_f32_e32 v21, v9, v21
	s_waitcnt lgkmcnt(0)
	v_fma_f32 v22, v9, v22, v12
	v_cndmask_b32_e64 v9, v21, v9, s[8:9]
	v_cndmask_b32_e64 v12, v22, v12, s[8:9]
	v_mov_b32_dpp v21, v13 row_shr:4 row_mask:0xf bank_mask:0xf
	v_mov_b32_dpp v22, v16 row_shr:4 row_mask:0xf bank_mask:0xf
	s_waitcnt lgkmcnt(1)
	v_mul_f32_e32 v21, v13, v21
	s_waitcnt lgkmcnt(0)
	v_fma_f32 v22, v13, v22, v16
	v_cndmask_b32_e64 v13, v21, v13, s[8:9]
	v_cndmask_b32_e64 v16, v22, v16, s[8:9]
	v_mov_b32_dpp v21, v17 row_shr:4 row_mask:0xf bank_mask:0xf
	v_mov_b32_dpp v22, v18 row_shr:4 row_mask:0xf bank_mask:0xf
	s_waitcnt lgkmcnt(1)
	v_mul_f32_e32 v21, v17, v21
	s_waitcnt lgkmcnt(0)
	v_fma_f32 v22, v17, v22, v18
	v_cndmask_b32_e64 v17, v21, v17, s[8:9]
	v_cndmask_b32_e64 v18, v22, v18, s[8:9]
	v_mov_b32_dpp v21, v19 row_shr:4 row_mask:0xf bank_mask:0xf
	v_mov_b32_dpp v22, v20 row_shr:4 row_mask:0xf bank_mask:0xf
	s_waitcnt lgkmcnt(1)
	v_mul_f32_e32 v21, v19, v21
	s_waitcnt lgkmcnt(0)
	v_fma_f32 v22, v19, v22, v20
	v_cndmask_b32_e64 v19, v21, v19, s[8:9]
	v_cndmask_b32_e64 v20, v22, v20, s[8:9]
	v_add_u32_e32 v21, -8, v191
	v_cmp_lt_i32_e64 s[10:11], v21, v8
	s_nop 1
	v_cndmask_b32_e64 v21, v21, v191, s[10:11]
	v_lshlrev_b32_e32 v168, 2, v21
	v_mov_b32_dpp v21, v9 row_shr:8 row_mask:0xf bank_mask:0xf
	v_mov_b32_dpp v22, v12 row_shr:8 row_mask:0xf bank_mask:0xf
	v_cmp_gt_u32_e64 s[10:11], 8, v165
	s_waitcnt lgkmcnt(1)
	v_mul_f32_e32 v21, v9, v21
	s_waitcnt lgkmcnt(0)
	v_fma_f32 v22, v9, v22, v12
	v_cndmask_b32_e64 v140, v21, v9, s[10:11]
	v_cndmask_b32_e64 v138, v22, v12, s[10:11]
	v_mov_b32_dpp v9, v13 row_shr:8 row_mask:0xf bank_mask:0xf
	v_mov_b32_dpp v12, v16 row_shr:8 row_mask:0xf bank_mask:0xf
	s_waitcnt lgkmcnt(1)
	v_mul_f32_e32 v9, v13, v9
	s_waitcnt lgkmcnt(0)
	v_fma_f32 v12, v13, v12, v16
	v_cndmask_b32_e64 v141, v9, v13, s[10:11]
	v_cndmask_b32_e64 v139, v12, v16, s[10:11]
	v_mov_b32_dpp v9, v17 row_shr:8 row_mask:0xf bank_mask:0xf
	v_mov_b32_dpp v12, v18 row_shr:8 row_mask:0xf bank_mask:0xf
	s_waitcnt lgkmcnt(1)
	v_mul_f32_e32 v9, v17, v9
	s_waitcnt lgkmcnt(0)
	v_fma_f32 v12, v17, v12, v18
	v_cndmask_b32_e64 v144, v9, v17, s[10:11]
	v_cndmask_b32_e64 v142, v12, v18, s[10:11]
	v_mov_b32_dpp v9, v19 row_shr:8 row_mask:0xf bank_mask:0xf
	v_mov_b32_dpp v12, v20 row_shr:8 row_mask:0xf bank_mask:0xf
	s_waitcnt lgkmcnt(1)
	v_mul_f32_e32 v9, v19, v9
	s_waitcnt lgkmcnt(0)
	v_fma_f32 v12, v19, v12, v20
	v_cndmask_b32_e64 v145, v9, v19, s[10:11]
	v_cndmask_b32_e64 v143, v12, v20, s[10:11]
	v_pk_mul_f32 v[12:13], v[32:33], v[60:61]
	v_add_u32_e32 v9, -16, v191
	v_pk_mul_f32 v[12:13], v[12:13], v[64:65]
	s_nop 1
	v_mov_b32_dpp v16, v12 row_shr:1 row_mask:0xf bank_mask:0xf
	v_mov_b32_dpp v17, v13 row_shr:1 row_mask:0xf bank_mask:0xf
	v_pk_mul_f32 v[10:11], v[62:63], v[10:11]
	v_cmp_lt_i32_e64 s[12:13], v9, v8
	v_cndmask_b32_e32 v11, v11, v63, vcc
	v_cndmask_b32_e32 v10, v10, v62, vcc
	s_waitcnt lgkmcnt(0)
	v_pk_fma_f32 v[16:17], v[62:63], v[16:17], v[12:13]
	v_cndmask_b32_e64 v8, v9, v191, s[12:13]
	v_cndmask_b32_e32 v17, v17, v13, vcc
	v_cndmask_b32_e32 v16, v16, v12, vcc
	v_mov_b32_dpp v20, v10 row_shr:2 row_mask:0xf bank_mask:0xf
	s_nop 1
	v_mov_b32_dpp v22, v16 row_shr:2 row_mask:0xf bank_mask:0xf
	v_mov_b32_dpp v21, v11 row_shr:2 row_mask:0xf bank_mask:0xf
	v_mov_b32_dpp v23, v17 row_shr:2 row_mask:0xf bank_mask:0xf
	v_lshlrev_b32_e32 v170, 2, v8
	v_mov_b32_dpp v18, v138 row_bcast:15 row_mask:0xa bank_mask:0xf
	v_mov_b32_dpp v19, v139 row_bcast:15 row_mask:0xa bank_mask:0xf
	s_waitcnt lgkmcnt(3)
	v_pk_mul_f32 v[20:21], v[10:11], v[20:21]
	s_waitcnt lgkmcnt(2)
	v_pk_fma_f32 v[22:23], v[10:11], v[22:23], v[16:17]
	v_cndmask_b32_e64 v21, v21, v11, s[6:7]
	v_cndmask_b32_e64 v20, v20, v10, s[6:7]
	v_cndmask_b32_e64 v17, v23, v17, s[6:7]
	v_cndmask_b32_e64 v16, v22, v16, s[6:7]
	s_waitcnt lgkmcnt(0)
	v_pk_fma_f32 v[12:13], v[140:141], v[18:19], v[138:139]
	v_mov_b32_dpp v18, v144 row_bcast:15 row_mask:0xa bank_mask:0xf
	v_mov_b32_dpp v19, v145 row_bcast:15 row_mask:0xa bank_mask:0xf
	v_mov_b32_dpp v22, v20 row_shr:4 row_mask:0xf bank_mask:0xf
	v_mov_b32_dpp v32, v16 row_shr:4 row_mask:0xf bank_mask:0xf
	v_mov_b32_dpp v23, v21 row_shr:4 row_mask:0xf bank_mask:0xf
	v_mov_b32_dpp v33, v17 row_shr:4 row_mask:0xf bank_mask:0xf
	s_waitcnt lgkmcnt(4)
	v_pk_mul_f32 v[10:11], v[144:145], v[18:19]
	v_pk_mul_f32 v[14:15], v[68:69], v[14:15]
	v_mov_b32_dpp v8, v140 row_bcast:15 row_mask:0xa bank_mask:0xf
	s_waitcnt lgkmcnt(2)
	v_pk_mul_f32 v[18:19], v[20:21], v[22:23]
	s_waitcnt lgkmcnt(1)
	v_pk_fma_f32 v[22:23], v[20:21], v[32:33], v[16:17]
	v_cndmask_b32_e64 v19, v19, v21, s[8:9]
	v_cndmask_b32_e64 v17, v23, v17, s[8:9]
	v_cndmask_b32_e64 v16, v22, v16, s[8:9]
	v_pk_mul_f32 v[22:23], v[34:35], v[66:67]
	v_cndmask_b32_e64 v18, v18, v20, s[8:9]
	v_pk_mul_f32 v[22:23], v[22:23], v[70:71]
	s_nop 1
	v_mov_b32_dpp v32, v22 row_shr:1 row_mask:0xf bank_mask:0xf
	v_mov_b32_dpp v33, v23 row_shr:1 row_mask:0xf bank_mask:0xf
	v_mov_b32_dpp v20, v18 row_shr:8 row_mask:0xf bank_mask:0xf
	v_mov_b32_dpp v21, v19 row_shr:8 row_mask:0xf bank_mask:0xf
	v_cndmask_b32_e32 v15, v15, v69, vcc
	v_cndmask_b32_e32 v14, v14, v68, vcc
	s_waitcnt lgkmcnt(2)
	v_pk_fma_f32 v[32:33], v[68:69], v[32:33], v[22:23]
	v_mov_b32_dpp v34, v16 row_shr:8 row_mask:0xf bank_mask:0xf
	v_cndmask_b32_e32 v23, v33, v23, vcc
	v_cndmask_b32_e32 v22, v32, v22, vcc
	v_mov_b32_dpp v35, v17 row_shr:8 row_mask:0xf bank_mask:0xf
	v_mov_b32_dpp v32, v14 row_shr:2 row_mask:0xf bank_mask:0xf
	v_mov_b32_dpp v62, v22 row_shr:2 row_mask:0xf bank_mask:0xf
	v_mov_b32_dpp v33, v15 row_shr:2 row_mask:0xf bank_mask:0xf
	v_mov_b32_dpp v63, v23 row_shr:2 row_mask:0xf bank_mask:0xf
	s_waitcnt lgkmcnt(6)
	v_pk_mul_f32 v[20:21], v[18:19], v[20:21]
	s_waitcnt lgkmcnt(4)
	v_pk_fma_f32 v[34:35], v[18:19], v[34:35], v[16:17]
	v_cndmask_b32_e64 v65, v21, v19, s[10:11]
	v_cndmask_b32_e64 v64, v20, v18, s[10:11]
	s_waitcnt lgkmcnt(1)
	v_pk_mul_f32 v[18:19], v[14:15], v[32:33]
	s_waitcnt lgkmcnt(0)
	v_pk_fma_f32 v[20:21], v[14:15], v[62:63], v[22:23]
	v_cndmask_b32_e64 v15, v19, v15, s[6:7]
	v_cndmask_b32_e64 v14, v18, v14, s[6:7]
	v_cndmask_b32_e64 v19, v21, v23, s[6:7]
	v_cndmask_b32_e64 v18, v20, v22, s[6:7]
	v_mov_b32_dpp v20, v14 row_shr:4 row_mask:0xf bank_mask:0xf
	s_nop 1
	v_mov_b32_dpp v22, v18 row_shr:4 row_mask:0xf bank_mask:0xf
	v_mov_b32_dpp v21, v15 row_shr:4 row_mask:0xf bank_mask:0xf
	v_mov_b32_dpp v23, v19 row_shr:4 row_mask:0xf bank_mask:0xf
	v_cndmask_b32_e64 v67, v35, v17, s[10:11]
	v_cndmask_b32_e64 v66, v34, v16, s[10:11]
	v_mov_b32_dpp v9, v141 row_bcast:15 row_mask:0xa bank_mask:0xf
	s_waitcnt lgkmcnt(2)
	v_pk_mul_f32 v[20:21], v[14:15], v[20:21]
	s_waitcnt lgkmcnt(1)
	v_pk_fma_f32 v[22:23], v[14:15], v[22:23], v[18:19]
	v_cndmask_b32_e64 v15, v21, v15, s[8:9]
	v_cndmask_b32_e64 v14, v20, v14, s[8:9]
	v_cndmask_b32_e64 v19, v23, v19, s[8:9]
	v_cndmask_b32_e64 v18, v22, v18, s[8:9]
	v_mov_b32_dpp v20, v14 row_shr:8 row_mask:0xf bank_mask:0xf
	s_nop 1
	v_mov_b32_dpp v22, v18 row_shr:8 row_mask:0xf bank_mask:0xf
	v_mov_b32_dpp v21, v15 row_shr:8 row_mask:0xf bank_mask:0xf
	v_mov_b32_dpp v23, v19 row_shr:8 row_mask:0xf bank_mask:0xf
	v_mov_b32_dpp v60, v142 row_bcast:15 row_mask:0xa bank_mask:0xf
	v_mov_b32_dpp v61, v143 row_bcast:15 row_mask:0xa bank_mask:0xf
	v_mov_b32_dpp v16, v64 row_bcast:15 row_mask:0xa bank_mask:0xf
	s_waitcnt lgkmcnt(4)
	v_pk_mul_f32 v[20:21], v[14:15], v[20:21]
	s_waitcnt lgkmcnt(3)
	v_pk_fma_f32 v[22:23], v[14:15], v[22:23], v[18:19]
	v_cndmask_b32_e64 v69, v21, v15, s[10:11]
	v_cndmask_b32_e64 v68, v20, v14, s[10:11]
	v_cndmask_b32_e64 v71, v23, v19, s[10:11]
	v_cndmask_b32_e64 v70, v22, v18, s[10:11]
	v_mov_b32_dpp v32, v66 row_bcast:15 row_mask:0xa bank_mask:0xf
	v_mov_b32_dpp v17, v65 row_bcast:15 row_mask:0xa bank_mask:0xf
	v_mov_b32_dpp v33, v67 row_bcast:15 row_mask:0xa bank_mask:0xf
	v_mov_b32_dpp v18, v68 row_bcast:15 row_mask:0xa bank_mask:0xf
	v_mov_b32_dpp v34, v70 row_bcast:15 row_mask:0xa bank_mask:0xf
	v_mov_b32_dpp v19, v69 row_bcast:15 row_mask:0xa bank_mask:0xf
	v_mov_b32_dpp v35, v71 row_bcast:15 row_mask:0xa bank_mask:0xf
	v_pk_mul_f32 v[8:9], v[140:141], v[8:9]
	s_waitcnt lgkmcnt(8)
	v_pk_fma_f32 v[14:15], v[144:145], v[60:61], v[142:143]
	s_waitcnt lgkmcnt(5)
	v_pk_mul_f32 v[20:21], v[64:65], v[16:17]
	s_waitcnt lgkmcnt(4)
	v_pk_fma_f32 v[16:17], v[64:65], v[32:33], v[66:67]
	s_waitcnt lgkmcnt(1)
	v_pk_mul_f32 v[22:23], v[68:69], v[18:19]
	s_waitcnt lgkmcnt(0)
	v_pk_fma_f32 v[18:19], v[68:69], v[34:35], v[70:71]
	v_pk_mul_f32 v[32:33], v[36:37], v[72:73]
	v_pk_mul_f32 v[28:29], v[76:77], v[28:29]
	v_pk_mul_f32 v[32:33], v[32:33], v[80:81]
	s_nop 1
	v_mov_b32_dpp v34, v32 row_shr:1 row_mask:0xf bank_mask:0xf
	v_mov_b32_dpp v35, v33 row_shr:1 row_mask:0xf bank_mask:0xf
	v_cndmask_b32_e32 v29, v29, v77, vcc
	v_cndmask_b32_e32 v28, v28, v76, vcc
	v_pk_mul_f32 v[38:39], v[38:39], v[74:75]
	v_pk_mul_f32 v[24:25], v[78:79], v[24:25]
	s_waitcnt lgkmcnt(0)
	v_pk_fma_f32 v[34:35], v[76:77], v[34:35], v[32:33]
	v_pk_mul_f32 v[38:39], v[38:39], v[82:83]
	v_cndmask_b32_e32 v33, v35, v33, vcc
	v_cndmask_b32_e32 v32, v34, v32, vcc
	v_mov_b32_dpp v34, v28 row_shr:2 row_mask:0xf bank_mask:0xf
	v_mov_b32_dpp v35, v29 row_shr:2 row_mask:0xf bank_mask:0xf
	v_mov_b32_dpp v36, v32 row_shr:2 row_mask:0xf bank_mask:0xf
	v_mov_b32_dpp v37, v33 row_shr:2 row_mask:0xf bank_mask:0xf
	v_mov_b32_dpp v60, v38 row_shr:1 row_mask:0xf bank_mask:0xf
	v_mov_b32_dpp v61, v39 row_shr:1 row_mask:0xf bank_mask:0xf
	s_waitcnt lgkmcnt(4)
	v_pk_mul_f32 v[34:35], v[28:29], v[34:35]
	v_cndmask_b32_e32 v25, v25, v79, vcc
	s_waitcnt lgkmcnt(2)
	v_pk_fma_f32 v[36:37], v[28:29], v[36:37], v[32:33]
	v_cndmask_b32_e64 v29, v35, v29, s[6:7]
	v_cndmask_b32_e64 v28, v34, v28, s[6:7]
	v_cndmask_b32_e64 v33, v37, v33, s[6:7]
	v_cndmask_b32_e64 v32, v36, v32, s[6:7]
	v_mov_b32_dpp v34, v28 row_shr:4 row_mask:0xf bank_mask:0xf
	v_mov_b32_dpp v35, v29 row_shr:4 row_mask:0xf bank_mask:0xf
	v_mov_b32_dpp v36, v32 row_shr:4 row_mask:0xf bank_mask:0xf
	v_mov_b32_dpp v37, v33 row_shr:4 row_mask:0xf bank_mask:0xf
	v_cndmask_b32_e32 v24, v24, v78, vcc
	v_pk_mul_f32 v[40:41], v[40:41], v[84:85]
	s_waitcnt lgkmcnt(2)
	v_pk_mul_f32 v[34:35], v[28:29], v[34:35]
	v_pk_mul_f32 v[40:41], v[40:41], v[88:89]
	s_waitcnt lgkmcnt(0)
	v_pk_fma_f32 v[36:37], v[28:29], v[36:37], v[32:33]
	v_cndmask_b32_e64 v29, v35, v29, s[8:9]
	v_cndmask_b32_e64 v28, v34, v28, s[8:9]
	s_nop 1
	v_mov_b32_dpp v34, v28 row_shr:8 row_mask:0xf bank_mask:0xf
	v_mov_b32_dpp v35, v29 row_shr:8 row_mask:0xf bank_mask:0xf
	v_cndmask_b32_e64 v33, v37, v33, s[8:9]
	v_cndmask_b32_e64 v32, v36, v32, s[8:9]
	s_nop 1
	v_mov_b32_dpp v36, v32 row_shr:8 row_mask:0xf bank_mask:0xf
	v_mov_b32_dpp v37, v33 row_shr:8 row_mask:0xf bank_mask:0xf
	s_waitcnt lgkmcnt(2)
	v_pk_mul_f32 v[34:35], v[28:29], v[34:35]
	v_pk_mul_f32 v[30:31], v[86:87], v[30:31]
	v_cndmask_b32_e64 v73, v35, v29, s[10:11]
	v_cndmask_b32_e64 v72, v34, v28, s[10:11]
	s_waitcnt lgkmcnt(0)
	v_pk_fma_f32 v[36:37], v[28:29], v[36:37], v[32:33]
	v_pk_fma_f32 v[28:29], v[78:79], v[60:61], v[38:39]
	v_mov_b32_dpp v34, v24 row_shr:2 row_mask:0xf bank_mask:0xf
	v_cndmask_b32_e32 v29, v29, v39, vcc
	v_cndmask_b32_e32 v28, v28, v38, vcc
	v_mov_b32_dpp v35, v25 row_shr:2 row_mask:0xf bank_mask:0xf
	s_nop 1
	v_mov_b32_dpp v38, v28 row_shr:2 row_mask:0xf bank_mask:0xf
	v_mov_b32_dpp v39, v29 row_shr:2 row_mask:0xf bank_mask:0xf
	v_cndmask_b32_e64 v75, v37, v33, s[10:11]
	v_cndmask_b32_e64 v74, v36, v32, s[10:11]
	s_waitcnt lgkmcnt(2)
	v_pk_mul_f32 v[34:35], v[24:25], v[34:35]
	v_mov_b32_dpp v32, v72 row_bcast:15 row_mask:0xa bank_mask:0xf
	s_waitcnt lgkmcnt(1)
	v_pk_fma_f32 v[36:37], v[24:25], v[38:39], v[28:29]
	v_cndmask_b32_e64 v25, v35, v25, s[6:7]
	v_cndmask_b32_e64 v24, v34, v24, s[6:7]
	s_nop 1
	v_mov_b32_dpp v34, v24 row_shr:4 row_mask:0xf bank_mask:0xf
	v_mov_b32_dpp v35, v25 row_shr:4 row_mask:0xf bank_mask:0xf
	v_cndmask_b32_e64 v29, v37, v29, s[6:7]
	v_cndmask_b32_e64 v28, v36, v28, s[6:7]
	s_nop 1
	v_mov_b32_dpp v36, v28 row_shr:4 row_mask:0xf bank_mask:0xf
	v_mov_b32_dpp v37, v29 row_shr:4 row_mask:0xf bank_mask:0xf
	s_waitcnt lgkmcnt(2)
	v_pk_mul_f32 v[34:35], v[24:25], v[34:35]
	v_mov_b32_dpp v33, v73 row_bcast:15 row_mask:0xa bank_mask:0xf
	v_cndmask_b32_e64 v35, v35, v25, s[8:9]
	v_cndmask_b32_e64 v34, v34, v24, s[8:9]
	s_nop 1
	v_mov_b32_dpp v60, v34 row_shr:8 row_mask:0xf bank_mask:0xf
	v_mov_b32_dpp v61, v35 row_shr:8 row_mask:0xf bank_mask:0xf
	s_waitcnt lgkmcnt(3)
	v_pk_fma_f32 v[36:37], v[24:25], v[36:37], v[28:29]
	v_mov_b32_dpp v38, v74 row_bcast:15 row_mask:0xa bank_mask:0xf
	v_cndmask_b32_e64 v37, v37, v29, s[8:9]
	v_cndmask_b32_e64 v36, v36, v28, s[8:9]
	s_waitcnt lgkmcnt(3)
	v_pk_mul_f32 v[28:29], v[72:73], v[32:33]
	s_waitcnt lgkmcnt(1)
	v_pk_mul_f32 v[32:33], v[34:35], v[60:61]
	v_mov_b32_dpp v60, v40 row_shr:1 row_mask:0xf bank_mask:0xf
	v_mov_b32_dpp v61, v41 row_shr:1 row_mask:0xf bank_mask:0xf
	v_mov_b32_dpp v39, v75 row_bcast:15 row_mask:0xa bank_mask:0xf
	v_mov_b32_dpp v62, v36 row_shr:8 row_mask:0xf bank_mask:0xf
	v_mov_b32_dpp v63, v37 row_shr:8 row_mask:0xf bank_mask:0xf
	v_cndmask_b32_e64 v79, v33, v35, s[10:11]
	v_cndmask_b32_e64 v78, v32, v34, s[10:11]
	s_waitcnt lgkmcnt(3)
	v_pk_fma_f32 v[32:33], v[86:87], v[60:61], v[40:41]
	v_cndmask_b32_e32 v31, v31, v87, vcc
	v_cndmask_b32_e32 v30, v30, v86, vcc
	v_cndmask_b32_e32 v33, v33, v41, vcc
	v_cndmask_b32_e32 v32, v32, v40, vcc
	s_waitcnt lgkmcnt(2)
	v_pk_fma_f32 v[24:25], v[72:73], v[38:39], v[74:75]
	s_waitcnt lgkmcnt(0)
	v_pk_fma_f32 v[38:39], v[34:35], v[62:63], v[36:37]
	v_mov_b32_dpp v34, v30 row_shr:2 row_mask:0xf bank_mask:0xf
	v_mov_b32_dpp v40, v32 row_shr:2 row_mask:0xf bank_mask:0xf
	v_mov_b32_dpp v35, v31 row_shr:2 row_mask:0xf bank_mask:0xf
	v_mov_b32_dpp v41, v33 row_shr:2 row_mask:0xf bank_mask:0xf
	v_cndmask_b32_e64 v77, v39, v37, s[10:11]
	v_cndmask_b32_e64 v76, v38, v36, s[10:11]
	v_mov_b32_dpp v36, v78 row_bcast:15 row_mask:0xa bank_mask:0xf
	s_waitcnt lgkmcnt(2)
	v_pk_mul_f32 v[34:35], v[30:31], v[34:35]
	s_waitcnt lgkmcnt(1)
	v_pk_fma_f32 v[38:39], v[30:31], v[40:41], v[32:33]
	v_cndmask_b32_e64 v35, v35, v31, s[6:7]
	v_cndmask_b32_e64 v34, v34, v30, s[6:7]
	v_cndmask_b32_e64 v33, v39, v33, s[6:7]
	v_cndmask_b32_e64 v32, v38, v32, s[6:7]
	v_mov_b32_dpp v37, v79 row_bcast:15 row_mask:0xa bank_mask:0xf
	v_mov_b32_dpp v38, v34 row_shr:4 row_mask:0xf bank_mask:0xf
	v_mov_b32_dpp v40, v32 row_shr:4 row_mask:0xf bank_mask:0xf
	v_mov_b32_dpp v39, v35 row_shr:4 row_mask:0xf bank_mask:0xf
	v_mov_b32_dpp v41, v33 row_shr:4 row_mask:0xf bank_mask:0xf
	s_waitcnt lgkmcnt(4)
	v_pk_mul_f32 v[30:31], v[78:79], v[36:37]
	v_pk_mul_f32 v[26:27], v[92:93], v[26:27]
	v_mov_b32_dpp v60, v76 row_bcast:15 row_mask:0xa bank_mask:0xf
	s_waitcnt lgkmcnt(2)
	v_pk_mul_f32 v[36:37], v[34:35], v[38:39]
	s_waitcnt lgkmcnt(1)
	v_pk_fma_f32 v[38:39], v[34:35], v[40:41], v[32:33]
	v_cndmask_b32_e64 v35, v37, v35, s[8:9]
	v_cndmask_b32_e64 v33, v39, v33, s[8:9]
	v_cndmask_b32_e64 v32, v38, v32, s[8:9]
	v_pk_mul_f32 v[38:39], v[42:43], v[90:91]
	v_cndmask_b32_e64 v34, v36, v34, s[8:9]
	v_pk_mul_f32 v[38:39], v[38:39], v[94:95]
	s_nop 1
	v_mov_b32_dpp v40, v38 row_shr:1 row_mask:0xf bank_mask:0xf
	v_mov_b32_dpp v41, v39 row_shr:1 row_mask:0xf bank_mask:0xf
	v_mov_b32_dpp v36, v34 row_shr:8 row_mask:0xf bank_mask:0xf
	v_mov_b32_dpp v37, v35 row_shr:8 row_mask:0xf bank_mask:0xf
	v_cndmask_b32_e32 v27, v27, v93, vcc
	v_cndmask_b32_e32 v26, v26, v92, vcc
	s_waitcnt lgkmcnt(2)
	v_pk_fma_f32 v[40:41], v[92:93], v[40:41], v[38:39]
	v_mov_b32_dpp v42, v32 row_shr:8 row_mask:0xf bank_mask:0xf
	v_cndmask_b32_e32 v39, v41, v39, vcc
	v_cndmask_b32_e32 v38, v40, v38, vcc
	v_mov_b32_dpp v43, v33 row_shr:8 row_mask:0xf bank_mask:0xf
	v_mov_b32_dpp v40, v26 row_shr:2 row_mask:0xf bank_mask:0xf
	v_mov_b32_dpp v62, v38 row_shr:2 row_mask:0xf bank_mask:0xf
	v_mov_b32_dpp v41, v27 row_shr:2 row_mask:0xf bank_mask:0xf
	v_mov_b32_dpp v63, v39 row_shr:2 row_mask:0xf bank_mask:0xf
	s_waitcnt lgkmcnt(6)
	v_pk_mul_f32 v[36:37], v[34:35], v[36:37]
	s_waitcnt lgkmcnt(4)
	v_pk_fma_f32 v[42:43], v[34:35], v[42:43], v[32:33]
	v_cndmask_b32_e64 v81, v37, v35, s[10:11]
	v_cndmask_b32_e64 v80, v36, v34, s[10:11]
	s_waitcnt lgkmcnt(1)
	v_pk_mul_f32 v[34:35], v[26:27], v[40:41]
	s_waitcnt lgkmcnt(0)
	v_pk_fma_f32 v[36:37], v[26:27], v[62:63], v[38:39]
	v_cndmask_b32_e64 v27, v35, v27, s[6:7]
	v_cndmask_b32_e64 v26, v34, v26, s[6:7]
	v_cndmask_b32_e64 v35, v37, v39, s[6:7]
	v_cndmask_b32_e64 v34, v36, v38, s[6:7]
	v_mov_b32_dpp v36, v26 row_shr:4 row_mask:0xf bank_mask:0xf
	s_nop 1
	v_mov_b32_dpp v38, v34 row_shr:4 row_mask:0xf bank_mask:0xf
	v_mov_b32_dpp v37, v27 row_shr:4 row_mask:0xf bank_mask:0xf
	v_mov_b32_dpp v39, v35 row_shr:4 row_mask:0xf bank_mask:0xf
	v_cndmask_b32_e64 v83, v43, v33, s[10:11]
	v_cndmask_b32_e64 v82, v42, v32, s[10:11]
	v_mov_b32_dpp v61, v77 row_bcast:15 row_mask:0xa bank_mask:0xf
	s_waitcnt lgkmcnt(2)
	v_pk_mul_f32 v[36:37], v[26:27], v[36:37]
	s_waitcnt lgkmcnt(1)
	v_pk_fma_f32 v[38:39], v[26:27], v[38:39], v[34:35]
	v_cndmask_b32_e64 v27, v37, v27, s[8:9]
	v_cndmask_b32_e64 v26, v36, v26, s[8:9]
	v_cndmask_b32_e64 v35, v39, v35, s[8:9]
	v_cndmask_b32_e64 v34, v38, v34, s[8:9]
	v_mov_b32_dpp v36, v26 row_shr:8 row_mask:0xf bank_mask:0xf
	s_nop 1
	v_mov_b32_dpp v38, v34 row_shr:8 row_mask:0xf bank_mask:0xf
	v_mov_b32_dpp v37, v27 row_shr:8 row_mask:0xf bank_mask:0xf
	v_mov_b32_dpp v39, v35 row_shr:8 row_mask:0xf bank_mask:0xf
	v_mov_b32_dpp v32, v80 row_bcast:15 row_mask:0xa bank_mask:0xf
	v_mov_b32_dpp v40, v82 row_bcast:15 row_mask:0xa bank_mask:0xf
	v_mov_b32_dpp v33, v81 row_bcast:15 row_mask:0xa bank_mask:0xf
	s_waitcnt lgkmcnt(4)
	v_pk_mul_f32 v[36:37], v[26:27], v[36:37]
	s_waitcnt lgkmcnt(3)
	v_pk_fma_f32 v[38:39], v[26:27], v[38:39], v[34:35]
	v_cndmask_b32_e64 v85, v37, v27, s[10:11]
	v_cndmask_b32_e64 v84, v36, v26, s[10:11]
	v_cndmask_b32_e64 v87, v39, v35, s[10:11]
	v_cndmask_b32_e64 v86, v38, v34, s[10:11]
	v_mov_b32_dpp v41, v83 row_bcast:15 row_mask:0xa bank_mask:0xf
	v_mov_b32_dpp v34, v84 row_bcast:15 row_mask:0xa bank_mask:0xf
	v_mov_b32_dpp v42, v86 row_bcast:15 row_mask:0xa bank_mask:0xf
	v_mov_b32_dpp v35, v85 row_bcast:15 row_mask:0xa bank_mask:0xf
	v_mov_b32_dpp v43, v87 row_bcast:15 row_mask:0xa bank_mask:0xf
	v_pk_fma_f32 v[26:27], v[78:79], v[60:61], v[76:77]
	s_waitcnt lgkmcnt(5)
	v_pk_mul_f32 v[36:37], v[80:81], v[32:33]
	s_waitcnt lgkmcnt(4)
	v_pk_fma_f32 v[32:33], v[80:81], v[40:41], v[82:83]
	s_waitcnt lgkmcnt(1)
	v_pk_mul_f32 v[38:39], v[84:85], v[34:35]
	s_waitcnt lgkmcnt(0)
	v_pk_fma_f32 v[34:35], v[84:85], v[42:43], v[86:87]
	v_pk_mul_f32 v[40:41], v[48:49], v[56:57]
	v_pk_mul_f32 v[48:49], v[96:97], v[158:159]
	v_pk_mul_f32 v[40:41], v[40:41], v[100:101]
	s_nop 1
	v_mov_b32_dpp v42, v40 row_shr:1 row_mask:0xf bank_mask:0xf
	v_mov_b32_dpp v43, v41 row_shr:1 row_mask:0xf bank_mask:0xf
	v_cndmask_b32_e32 v49, v49, v97, vcc
	v_cndmask_b32_e32 v48, v48, v96, vcc
	v_pk_mul_f32 v[50:51], v[50:51], v[58:59]
	v_pk_mul_f32 v[44:45], v[44:45], v[104:105]
	s_waitcnt lgkmcnt(0)
	v_pk_fma_f32 v[42:43], v[96:97], v[42:43], v[40:41]
	v_pk_mul_f32 v[50:51], v[50:51], v[102:103]
	v_cndmask_b32_e32 v41, v43, v41, vcc
	v_cndmask_b32_e32 v40, v42, v40, vcc
	v_mov_b32_dpp v42, v48 row_shr:2 row_mask:0xf bank_mask:0xf
	v_mov_b32_dpp v43, v49 row_shr:2 row_mask:0xf bank_mask:0xf
	v_mov_b32_dpp v56, v40 row_shr:2 row_mask:0xf bank_mask:0xf
	v_mov_b32_dpp v57, v41 row_shr:2 row_mask:0xf bank_mask:0xf
	v_mov_b32_dpp v58, v50 row_shr:1 row_mask:0xf bank_mask:0xf
	v_mov_b32_dpp v59, v51 row_shr:1 row_mask:0xf bank_mask:0xf
	s_waitcnt lgkmcnt(4)
	v_pk_mul_f32 v[42:43], v[48:49], v[42:43]
	v_pk_mul_f32 v[44:45], v[44:45], v[106:107]
	s_waitcnt lgkmcnt(2)
	v_pk_fma_f32 v[56:57], v[48:49], v[56:57], v[40:41]
	v_cndmask_b32_e64 v43, v43, v49, s[6:7]
	v_cndmask_b32_e64 v42, v42, v48, s[6:7]
	v_cndmask_b32_e64 v41, v57, v41, s[6:7]
	v_cndmask_b32_e64 v40, v56, v40, s[6:7]
	v_mov_b32_dpp v48, v42 row_shr:4 row_mask:0xf bank_mask:0xf
	v_mov_b32_dpp v49, v43 row_shr:4 row_mask:0xf bank_mask:0xf
	v_mov_b32_dpp v56, v40 row_shr:4 row_mask:0xf bank_mask:0xf
	v_mov_b32_dpp v57, v41 row_shr:4 row_mask:0xf bank_mask:0xf
	v_pk_mul_f32 v[46:47], v[46:47], v[108:109]
	v_pk_mul_f32 v[62:63], v[54:55], v[152:153]
	s_waitcnt lgkmcnt(2)
	v_pk_mul_f32 v[48:49], v[42:43], v[48:49]
	v_pk_mul_f32 v[46:47], v[46:47], v[110:111]
	s_waitcnt lgkmcnt(0)
	v_pk_fma_f32 v[56:57], v[42:43], v[56:57], v[40:41]
	v_cndmask_b32_e64 v43, v49, v43, s[8:9]
	v_cndmask_b32_e64 v42, v48, v42, s[8:9]
	s_nop 1
	v_mov_b32_dpp v48, v42 row_shr:8 row_mask:0xf bank_mask:0xf
	v_mov_b32_dpp v49, v43 row_shr:8 row_mask:0xf bank_mask:0xf
	v_cndmask_b32_e64 v41, v57, v41, s[8:9]
	v_cndmask_b32_e64 v40, v56, v40, s[8:9]
	s_nop 1
	v_mov_b32_dpp v56, v40 row_shr:8 row_mask:0xf bank_mask:0xf
	v_mov_b32_dpp v57, v41 row_shr:8 row_mask:0xf bank_mask:0xf
	s_waitcnt lgkmcnt(2)
	v_pk_mul_f32 v[48:49], v[42:43], v[48:49]
	s_waitcnt lgkmcnt(0)
	v_pk_fma_f32 v[56:57], v[42:43], v[56:57], v[40:41]
	v_cndmask_b32_e64 v89, v49, v43, s[10:11]
	v_cndmask_b32_e64 v88, v48, v42, s[10:11]
	v_pk_mul_f32 v[42:43], v[98:99], v[156:157]
	v_pk_fma_f32 v[48:49], v[98:99], v[58:59], v[50:51]
	v_cndmask_b32_e32 v43, v43, v99, vcc
	v_cndmask_b32_e32 v42, v42, v98, vcc
	v_cndmask_b32_e32 v49, v49, v51, vcc
	v_cndmask_b32_e32 v48, v48, v50, vcc
	v_mov_b32_dpp v50, v42 row_shr:2 row_mask:0xf bank_mask:0xf
	s_nop 1
	v_mov_b32_dpp v58, v48 row_shr:2 row_mask:0xf bank_mask:0xf
	v_mov_b32_dpp v51, v43 row_shr:2 row_mask:0xf bank_mask:0xf
	v_mov_b32_dpp v59, v49 row_shr:2 row_mask:0xf bank_mask:0xf
	v_cndmask_b32_e64 v91, v57, v41, s[10:11]
	v_cndmask_b32_e64 v90, v56, v40, s[10:11]
	v_mov_b32_dpp v40, v88 row_bcast:15 row_mask:0xa bank_mask:0xf
	s_waitcnt lgkmcnt(2)
	v_pk_mul_f32 v[50:51], v[42:43], v[50:51]
	s_waitcnt lgkmcnt(1)
	v_pk_fma_f32 v[56:57], v[42:43], v[58:59], v[48:49]
	v_cndmask_b32_e64 v43, v51, v43, s[6:7]
	v_cndmask_b32_e64 v42, v50, v42, s[6:7]
	v_cndmask_b32_e64 v49, v57, v49, s[6:7]
	v_cndmask_b32_e64 v48, v56, v48, s[6:7]
	v_mov_b32_dpp v50, v42 row_shr:4 row_mask:0xf bank_mask:0xf
	s_nop 1
	v_mov_b32_dpp v56, v48 row_shr:4 row_mask:0xf bank_mask:0xf
	v_mov_b32_dpp v51, v43 row_shr:4 row_mask:0xf bank_mask:0xf
	v_mov_b32_dpp v57, v49 row_shr:4 row_mask:0xf bank_mask:0xf
	v_mov_b32_dpp v58, v90 row_bcast:15 row_mask:0xa bank_mask:0xf
	v_mov_b32_dpp v41, v89 row_bcast:15 row_mask:0xa bank_mask:0xf
	v_mov_b32_dpp v59, v91 row_bcast:15 row_mask:0xa bank_mask:0xf
	s_waitcnt lgkmcnt(4)
	v_pk_mul_f32 v[50:51], v[42:43], v[50:51]
	s_waitcnt lgkmcnt(3)
	v_pk_fma_f32 v[56:57], v[42:43], v[56:57], v[48:49]
	v_cndmask_b32_e64 v43, v51, v43, s[8:9]
	v_cndmask_b32_e64 v42, v50, v42, s[8:9]
	v_cndmask_b32_e64 v51, v57, v49, s[8:9]
	v_cndmask_b32_e64 v50, v56, v48, s[8:9]
	s_nop 1
	v_mov_b32_dpp v60, v50 row_shr:8 row_mask:0xf bank_mask:0xf
	v_mov_b32_dpp v61, v51 row_shr:8 row_mask:0xf bank_mask:0xf
	v_mov_b32_dpp v56, v42 row_shr:8 row_mask:0xf bank_mask:0xf
	v_mov_b32_dpp v57, v43 row_shr:8 row_mask:0xf bank_mask:0xf
	s_waitcnt lgkmcnt(5)
	v_pk_mul_f32 v[48:49], v[88:89], v[40:41]
	s_waitcnt lgkmcnt(4)
	v_pk_fma_f32 v[40:41], v[88:89], v[58:59], v[90:91]
	s_waitcnt lgkmcnt(2)
	v_pk_fma_f32 v[58:59], v[42:43], v[60:61], v[50:51]
	v_mov_b32_dpp v60, v44 row_shr:1 row_mask:0xf bank_mask:0xf
	v_mov_b32_dpp v61, v45 row_shr:1 row_mask:0xf bank_mask:0xf
	s_waitcnt lgkmcnt(2)
	v_pk_mul_f32 v[56:57], v[42:43], v[56:57]
	v_cndmask_b32_e64 v93, v59, v51, s[10:11]
	v_cndmask_b32_e64 v95, v57, v43, s[10:11]
	v_cndmask_b32_e64 v94, v56, v42, s[10:11]
	s_waitcnt lgkmcnt(0)
	v_pk_fma_f32 v[56:57], v[52:53], v[60:61], v[44:45]
	v_pk_mul_f32 v[42:43], v[52:53], v[154:155]
	v_cndmask_b32_e32 v45, v57, v45, vcc
	v_cndmask_b32_e32 v44, v56, v44, vcc
	s_nop 1
	v_mov_b32_dpp v56, v44 row_shr:2 row_mask:0xf bank_mask:0xf
	v_mov_b32_dpp v57, v45 row_shr:2 row_mask:0xf bank_mask:0xf
	v_cndmask_b32_e32 v43, v43, v53, vcc
	v_cndmask_b32_e32 v42, v42, v52, vcc
	s_nop 1
	v_mov_b32_dpp v52, v42 row_shr:2 row_mask:0xf bank_mask:0xf
	v_mov_b32_dpp v53, v43 row_shr:2 row_mask:0xf bank_mask:0xf
	s_waitcnt lgkmcnt(2)
	v_pk_fma_f32 v[56:57], v[42:43], v[56:57], v[44:45]
	v_cndmask_b32_e64 v92, v58, v50, s[10:11]
	v_cndmask_b32_e64 v45, v57, v45, s[6:7]
	v_cndmask_b32_e64 v44, v56, v44, s[6:7]
	s_nop 1
	v_mov_b32_dpp v56, v44 row_shr:4 row_mask:0xf bank_mask:0xf
	v_mov_b32_dpp v57, v45 row_shr:4 row_mask:0xf bank_mask:0xf
	s_waitcnt lgkmcnt(2)
	v_pk_mul_f32 v[52:53], v[42:43], v[52:53]
	v_mov_b32_dpp v50, v94 row_bcast:15 row_mask:0xa bank_mask:0xf
	v_cndmask_b32_e64 v43, v53, v43, s[6:7]
	v_cndmask_b32_e64 v42, v52, v42, s[6:7]
	s_nop 1
	v_mov_b32_dpp v52, v42 row_shr:4 row_mask:0xf bank_mask:0xf
	v_mov_b32_dpp v53, v43 row_shr:4 row_mask:0xf bank_mask:0xf
	s_waitcnt lgkmcnt(3)
	v_pk_fma_f32 v[56:57], v[42:43], v[56:57], v[44:45]
	v_mov_b32_dpp v51, v95 row_bcast:15 row_mask:0xa bank_mask:0xf
	v_cndmask_b32_e64 v45, v57, v45, s[8:9]
	v_cndmask_b32_e64 v44, v56, v44, s[8:9]
	v_mov_b32_dpp v56, v46 row_shr:1 row_mask:0xf bank_mask:0xf
	v_mov_b32_dpp v57, v47 row_shr:1 row_mask:0xf bank_mask:0xf
	s_waitcnt lgkmcnt(3)
	v_pk_mul_f32 v[52:53], v[42:43], v[52:53]
	v_mov_b32_dpp v60, v44 row_shr:8 row_mask:0xf bank_mask:0xf
	v_cndmask_b32_e64 v43, v53, v43, s[8:9]
	v_cndmask_b32_e64 v42, v52, v42, s[8:9]
	s_waitcnt lgkmcnt(1)
	v_pk_fma_f32 v[56:57], v[54:55], v[56:57], v[46:47]
	v_mov_b32_dpp v52, v42 row_shr:8 row_mask:0xf bank_mask:0xf
	v_mov_b32_dpp v53, v43 row_shr:8 row_mask:0xf bank_mask:0xf
	v_cndmask_b32_e32 v55, v63, v55, vcc
	v_cndmask_b32_e32 v54, v62, v54, vcc
	v_cndmask_b32_e32 v47, v57, v47, vcc
	v_cndmask_b32_e32 v46, v56, v46, vcc
	v_mov_b32_dpp v61, v45 row_shr:8 row_mask:0xf bank_mask:0xf
	v_mov_b32_dpp v56, v54 row_shr:2 row_mask:0xf bank_mask:0xf
	v_mov_b32_dpp v62, v46 row_shr:2 row_mask:0xf bank_mask:0xf
	v_mov_b32_dpp v57, v55 row_shr:2 row_mask:0xf bank_mask:0xf
	v_mov_b32_dpp v63, v47 row_shr:2 row_mask:0xf bank_mask:0xf
	s_waitcnt lgkmcnt(5)
	v_pk_mul_f32 v[52:53], v[42:43], v[52:53]
	s_waitcnt lgkmcnt(4)
	v_pk_fma_f32 v[60:61], v[42:43], v[60:61], v[44:45]
	v_cndmask_b32_e64 v97, v53, v43, s[10:11]
	v_cndmask_b32_e64 v96, v52, v42, s[10:11]
	s_waitcnt lgkmcnt(1)
	v_pk_mul_f32 v[42:43], v[54:55], v[56:57]
	s_waitcnt lgkmcnt(0)
	v_pk_fma_f32 v[52:53], v[54:55], v[62:63], v[46:47]
	v_cndmask_b32_e64 v43, v43, v55, s[6:7]
	v_cndmask_b32_e64 v42, v42, v54, s[6:7]
	v_cndmask_b32_e64 v47, v53, v47, s[6:7]
	v_cndmask_b32_e64 v46, v52, v46, s[6:7]
	v_mov_b32_dpp v52, v42 row_shr:4 row_mask:0xf bank_mask:0xf
	s_nop 1
	v_mov_b32_dpp v54, v46 row_shr:4 row_mask:0xf bank_mask:0xf
	v_mov_b32_dpp v53, v43 row_shr:4 row_mask:0xf bank_mask:0xf
	v_mov_b32_dpp v55, v47 row_shr:4 row_mask:0xf bank_mask:0xf
	v_cndmask_b32_e64 v99, v61, v45, s[10:11]
	v_cndmask_b32_e64 v98, v60, v44, s[10:11]
	v_mov_b32_dpp v58, v92 row_bcast:15 row_mask:0xa bank_mask:0xf
	s_waitcnt lgkmcnt(2)
	v_pk_mul_f32 v[52:53], v[42:43], v[52:53]
	s_waitcnt lgkmcnt(1)
	v_pk_fma_f32 v[54:55], v[42:43], v[54:55], v[46:47]
	v_cndmask_b32_e64 v43, v53, v43, s[8:9]
	v_cndmask_b32_e64 v42, v52, v42, s[8:9]
	v_cndmask_b32_e64 v47, v55, v47, s[8:9]
	v_cndmask_b32_e64 v46, v54, v46, s[8:9]
	v_mov_b32_dpp v52, v42 row_shr:8 row_mask:0xf bank_mask:0xf
	s_nop 1
	v_mov_b32_dpp v54, v46 row_shr:8 row_mask:0xf bank_mask:0xf
	v_mov_b32_dpp v53, v43 row_shr:8 row_mask:0xf bank_mask:0xf
	v_mov_b32_dpp v55, v47 row_shr:8 row_mask:0xf bank_mask:0xf
	v_mov_b32_dpp v59, v93 row_bcast:15 row_mask:0xa bank_mask:0xf
	v_mov_b32_dpp v44, v96 row_bcast:15 row_mask:0xa bank_mask:0xf
	v_mov_b32_dpp v56, v98 row_bcast:15 row_mask:0xa bank_mask:0xf
	s_waitcnt lgkmcnt(4)
	v_pk_mul_f32 v[52:53], v[42:43], v[52:53]
	s_waitcnt lgkmcnt(3)
	v_pk_fma_f32 v[54:55], v[42:43], v[54:55], v[46:47]
	v_cndmask_b32_e64 v101, v53, v43, s[10:11]
	v_cndmask_b32_e64 v100, v52, v42, s[10:11]
	v_cndmask_b32_e64 v103, v55, v47, s[10:11]
	v_cndmask_b32_e64 v102, v54, v46, s[10:11]
	v_mov_b32_dpp v45, v97 row_bcast:15 row_mask:0xa bank_mask:0xf
	v_mov_b32_dpp v57, v99 row_bcast:15 row_mask:0xa bank_mask:0xf
	v_mov_b32_dpp v46, v100 row_bcast:15 row_mask:0xa bank_mask:0xf
	v_mov_b32_dpp v60, v102 row_bcast:15 row_mask:0xa bank_mask:0xf
	v_mov_b32_dpp v47, v101 row_bcast:15 row_mask:0xa bank_mask:0xf
	v_mov_b32_dpp v61, v103 row_bcast:15 row_mask:0xa bank_mask:0xf
	v_pk_mul_f32 v[50:51], v[94:95], v[50:51]
	s_waitcnt lgkmcnt(8)
	v_pk_fma_f32 v[42:43], v[94:95], v[58:59], v[92:93]
	s_waitcnt lgkmcnt(5)
	v_pk_mul_f32 v[52:53], v[96:97], v[44:45]
	s_waitcnt lgkmcnt(4)
	v_pk_fma_f32 v[44:45], v[96:97], v[56:57], v[98:99]
	s_waitcnt lgkmcnt(1)
	v_pk_mul_f32 v[54:55], v[100:101], v[46:47]
	s_waitcnt lgkmcnt(0)
	v_pk_fma_f32 v[46:47], v[100:101], v[60:61], v[102:103]
	v_pk_mul_f32 v[0:1], v[0:1], v[112:113]
	v_pk_mul_f32 v[58:59], v[116:117], v[150:151]
	v_pk_mul_f32 v[0:1], v[0:1], v[120:121]
	s_nop 1
	v_mov_b32_dpp v56, v0 row_shr:1 row_mask:0xf bank_mask:0xf
	v_mov_b32_dpp v57, v1 row_shr:1 row_mask:0xf bank_mask:0xf
	v_cndmask_b32_e32 v59, v59, v117, vcc
	v_cndmask_b32_e32 v58, v58, v116, vcc
	v_pk_mul_f32 v[2:3], v[2:3], v[114:115]
	v_pk_mul_f32 v[4:5], v[4:5], v[124:125]
	s_waitcnt lgkmcnt(0)
	v_pk_fma_f32 v[56:57], v[116:117], v[56:57], v[0:1]
	v_pk_mul_f32 v[2:3], v[2:3], v[122:123]
	v_cndmask_b32_e32 v1, v57, v1, vcc
	v_cndmask_b32_e32 v0, v56, v0, vcc
	v_mov_b32_dpp v56, v58 row_shr:2 row_mask:0xf bank_mask:0xf
	v_mov_b32_dpp v57, v59 row_shr:2 row_mask:0xf bank_mask:0xf
	v_mov_b32_dpp v60, v0 row_shr:2 row_mask:0xf bank_mask:0xf
	v_mov_b32_dpp v61, v1 row_shr:2 row_mask:0xf bank_mask:0xf
	v_mov_b32_dpp v62, v2 row_shr:1 row_mask:0xf bank_mask:0xf
	v_mov_b32_dpp v63, v3 row_shr:1 row_mask:0xf bank_mask:0xf
	s_waitcnt lgkmcnt(4)
	v_pk_mul_f32 v[56:57], v[58:59], v[56:57]
	v_pk_mul_f32 v[4:5], v[4:5], v[128:129]
	s_waitcnt lgkmcnt(2)
	v_pk_fma_f32 v[60:61], v[58:59], v[60:61], v[0:1]
	v_cndmask_b32_e64 v57, v57, v59, s[6:7]
	v_cndmask_b32_e64 v56, v56, v58, s[6:7]
	v_cndmask_b32_e64 v1, v61, v1, s[6:7]
	v_cndmask_b32_e64 v0, v60, v0, s[6:7]
	v_mov_b32_dpp v58, v56 row_shr:4 row_mask:0xf bank_mask:0xf
	v_mov_b32_dpp v59, v57 row_shr:4 row_mask:0xf bank_mask:0xf
	v_mov_b32_dpp v60, v0 row_shr:4 row_mask:0xf bank_mask:0xf
	v_mov_b32_dpp v61, v1 row_shr:4 row_mask:0xf bank_mask:0xf
	v_mov_b32_dpp v112, v4 row_shr:1 row_mask:0xf bank_mask:0xf
	v_mov_b32_dpp v113, v5 row_shr:1 row_mask:0xf bank_mask:0xf
	s_waitcnt lgkmcnt(4)
	v_pk_mul_f32 v[58:59], v[56:57], v[58:59]
	v_pk_mul_f32 v[6:7], v[6:7], v[130:131]
	s_waitcnt lgkmcnt(2)
	v_pk_fma_f32 v[60:61], v[56:57], v[60:61], v[0:1]
	v_cndmask_b32_e64 v57, v59, v57, s[8:9]
	v_cndmask_b32_e64 v56, v58, v56, s[8:9]
	s_nop 1
	v_mov_b32_dpp v58, v56 row_shr:8 row_mask:0xf bank_mask:0xf
	v_mov_b32_dpp v59, v57 row_shr:8 row_mask:0xf bank_mask:0xf
	v_cndmask_b32_e64 v1, v61, v1, s[8:9]
	v_cndmask_b32_e64 v0, v60, v0, s[8:9]
	s_nop 1
	v_mov_b32_dpp v60, v0 row_shr:8 row_mask:0xf bank_mask:0xf
	v_mov_b32_dpp v61, v1 row_shr:8 row_mask:0xf bank_mask:0xf
	s_waitcnt lgkmcnt(2)
	v_pk_mul_f32 v[58:59], v[56:57], v[58:59]
	v_pk_mul_f32 v[6:7], v[6:7], v[134:135]
	v_cndmask_b32_e64 v105, v59, v57, s[10:11]
	v_cndmask_b32_e64 v104, v58, v56, s[10:11]
	s_waitcnt lgkmcnt(0)
	v_pk_fma_f32 v[60:61], v[56:57], v[60:61], v[0:1]
	v_pk_mul_f32 v[56:57], v[118:119], v[148:149]
	v_pk_fma_f32 v[58:59], v[118:119], v[62:63], v[2:3]
	v_cndmask_b32_e32 v57, v57, v119, vcc
	v_cndmask_b32_e32 v56, v56, v118, vcc
	v_cndmask_b32_e32 v3, v59, v3, vcc
	v_cndmask_b32_e32 v2, v58, v2, vcc
	v_mov_b32_dpp v58, v56 row_shr:2 row_mask:0xf bank_mask:0xf
	v_mov_b32_dpp v59, v57 row_shr:2 row_mask:0xf bank_mask:0xf
	v_mov_b32_dpp v62, v2 row_shr:2 row_mask:0xf bank_mask:0xf
	v_mov_b32_dpp v63, v3 row_shr:2 row_mask:0xf bank_mask:0xf
	v_cndmask_b32_e64 v107, v61, v1, s[10:11]
	v_cndmask_b32_e64 v106, v60, v0, s[10:11]
	s_waitcnt lgkmcnt(2)
	v_pk_mul_f32 v[58:59], v[56:57], v[58:59]
	v_mov_b32_dpp v0, v104 row_bcast:15 row_mask:0xa bank_mask:0xf
	s_waitcnt lgkmcnt(1)
	v_pk_fma_f32 v[60:61], v[56:57], v[62:63], v[2:3]
	v_cndmask_b32_e64 v57, v59, v57, s[6:7]
	v_cndmask_b32_e64 v56, v58, v56, s[6:7]
	v_cndmask_b32_e64 v3, v61, v3, s[6:7]
	v_cndmask_b32_e64 v2, v60, v2, s[6:7]
	v_mov_b32_dpp v58, v56 row_shr:4 row_mask:0xf bank_mask:0xf
	v_mov_b32_dpp v59, v57 row_shr:4 row_mask:0xf bank_mask:0xf
	v_mov_b32_dpp v60, v2 row_shr:4 row_mask:0xf bank_mask:0xf
	v_mov_b32_dpp v61, v3 row_shr:4 row_mask:0xf bank_mask:0xf
	v_mov_b32_dpp v62, v106 row_bcast:15 row_mask:0xa bank_mask:0xf
	v_mov_b32_dpp v1, v105 row_bcast:15 row_mask:0xa bank_mask:0xf
	s_waitcnt lgkmcnt(4)
	v_pk_mul_f32 v[58:59], v[56:57], v[58:59]
	v_mov_b32_dpp v63, v107 row_bcast:15 row_mask:0xa bank_mask:0xf
	s_waitcnt lgkmcnt(3)
	v_pk_fma_f32 v[60:61], v[56:57], v[60:61], v[2:3]
	v_cndmask_b32_e64 v59, v59, v57, s[8:9]
	v_cndmask_b32_e64 v58, v58, v56, s[8:9]
	v_cndmask_b32_e64 v3, v61, v3, s[8:9]
	v_cndmask_b32_e64 v2, v60, v2, s[8:9]
	v_mov_b32_dpp v60, v58 row_shr:8 row_mask:0xf bank_mask:0xf
	v_mov_b32_dpp v61, v59 row_shr:8 row_mask:0xf bank_mask:0xf
	v_mov_b32_dpp v108, v2 row_shr:8 row_mask:0xf bank_mask:0xf
	v_mov_b32_dpp v109, v3 row_shr:8 row_mask:0xf bank_mask:0xf
	s_waitcnt lgkmcnt(5)
	v_pk_mul_f32 v[56:57], v[104:105], v[0:1]
	s_waitcnt lgkmcnt(4)
	v_pk_fma_f32 v[0:1], v[104:105], v[62:63], v[106:107]
	s_waitcnt lgkmcnt(2)
	v_pk_mul_f32 v[60:61], v[58:59], v[60:61]
	v_pk_mul_f32 v[114:115], v[132:133], v[136:137]
	s_waitcnt lgkmcnt(0)
	v_pk_fma_f32 v[62:63], v[58:59], v[108:109], v[2:3]
	v_cndmask_b32_e64 v111, v61, v59, s[10:11]
	v_cndmask_b32_e64 v110, v60, v58, s[10:11]
	v_pk_mul_f32 v[58:59], v[126:127], v[146:147]
	v_pk_fma_f32 v[60:61], v[126:127], v[112:113], v[4:5]
	v_cndmask_b32_e32 v59, v59, v127, vcc
	v_cndmask_b32_e32 v58, v58, v126, vcc
	v_cndmask_b32_e32 v5, v61, v5, vcc
	v_cndmask_b32_e32 v4, v60, v4, vcc
	v_mov_b32_dpp v60, v58 row_shr:2 row_mask:0xf bank_mask:0xf
	s_nop 1
	v_mov_b32_dpp v112, v4 row_shr:2 row_mask:0xf bank_mask:0xf
	v_mov_b32_dpp v61, v59 row_shr:2 row_mask:0xf bank_mask:0xf
	v_mov_b32_dpp v113, v5 row_shr:2 row_mask:0xf bank_mask:0xf
	v_cndmask_b32_e64 v109, v63, v3, s[10:11]
	v_cndmask_b32_e64 v108, v62, v2, s[10:11]
	v_mov_b32_dpp v2, v110 row_bcast:15 row_mask:0xa bank_mask:0xf
	s_waitcnt lgkmcnt(2)
	v_pk_mul_f32 v[60:61], v[58:59], v[60:61]
	s_waitcnt lgkmcnt(1)
	v_pk_fma_f32 v[62:63], v[58:59], v[112:113], v[4:5]
	v_cndmask_b32_e64 v61, v61, v59, s[6:7]
	v_cndmask_b32_e64 v60, v60, v58, s[6:7]
	v_cndmask_b32_e64 v5, v63, v5, s[6:7]
	v_cndmask_b32_e64 v4, v62, v4, s[6:7]
	v_mov_b32_dpp v3, v111 row_bcast:15 row_mask:0xa bank_mask:0xf
	v_mov_b32_dpp v62, v60 row_shr:4 row_mask:0xf bank_mask:0xf
	v_mov_b32_dpp v112, v4 row_shr:4 row_mask:0xf bank_mask:0xf
	v_mov_b32_dpp v63, v61 row_shr:4 row_mask:0xf bank_mask:0xf
	v_mov_b32_dpp v113, v5 row_shr:4 row_mask:0xf bank_mask:0xf
	s_waitcnt lgkmcnt(4)
	v_pk_mul_f32 v[58:59], v[110:111], v[2:3]
	v_cndmask_b32_e32 v115, v115, v133, vcc
	v_cndmask_b32_e32 v114, v114, v132, vcc
	s_waitcnt lgkmcnt(1)
	v_pk_mul_f32 v[2:3], v[60:61], v[62:63]
	s_waitcnt lgkmcnt(0)
	v_pk_fma_f32 v[62:63], v[60:61], v[112:113], v[4:5]
	v_cndmask_b32_e64 v3, v3, v61, s[8:9]
	v_cndmask_b32_e64 v5, v63, v5, s[8:9]
	v_cndmask_b32_e64 v4, v62, v4, s[8:9]
	v_mov_b32_dpp v62, v6 row_shr:1 row_mask:0xf bank_mask:0xf
	v_mov_b32_dpp v63, v7 row_shr:1 row_mask:0xf bank_mask:0xf
	v_cndmask_b32_e64 v2, v2, v60, s[8:9]
	s_nop 1
	v_mov_b32_dpp v60, v2 row_shr:8 row_mask:0xf bank_mask:0xf
	v_mov_b32_dpp v61, v3 row_shr:8 row_mask:0xf bank_mask:0xf
	v_mov_b32_dpp v112, v4 row_shr:8 row_mask:0xf bank_mask:0xf
	s_waitcnt lgkmcnt(3)
	v_pk_fma_f32 v[62:63], v[132:133], v[62:63], v[6:7]
	v_mov_b32_dpp v113, v5 row_shr:8 row_mask:0xf bank_mask:0xf
	v_cndmask_b32_e32 v7, v63, v7, vcc
	v_cndmask_b32_e32 v6, v62, v6, vcc
	v_mov_b32_dpp v62, v114 row_shr:2 row_mask:0xf bank_mask:0xf
	s_nop 1
	v_mov_b32_dpp v116, v6 row_shr:2 row_mask:0xf bank_mask:0xf
	v_mov_b32_dpp v63, v115 row_shr:2 row_mask:0xf bank_mask:0xf
	v_mov_b32_dpp v117, v7 row_shr:2 row_mask:0xf bank_mask:0xf
	s_waitcnt lgkmcnt(6)
	v_pk_mul_f32 v[60:61], v[2:3], v[60:61]
	s_waitcnt lgkmcnt(4)
	v_pk_fma_f32 v[118:119], v[2:3], v[112:113], v[4:5]
	v_cndmask_b32_e64 v113, v61, v3, s[10:11]
	v_cndmask_b32_e64 v112, v60, v2, s[10:11]
	s_waitcnt lgkmcnt(1)
	v_pk_mul_f32 v[2:3], v[114:115], v[62:63]
	s_waitcnt lgkmcnt(0)
	v_pk_fma_f32 v[60:61], v[114:115], v[116:117], v[6:7]
	v_cndmask_b32_e64 v3, v3, v115, s[6:7]
	v_cndmask_b32_e64 v2, v2, v114, s[6:7]
	v_cndmask_b32_e64 v7, v61, v7, s[6:7]
	v_cndmask_b32_e64 v6, v60, v6, s[6:7]
	v_mov_b32_dpp v60, v2 row_shr:4 row_mask:0xf bank_mask:0xf
	s_nop 1
	v_mov_b32_dpp v62, v6 row_shr:4 row_mask:0xf bank_mask:0xf
	v_mov_b32_dpp v61, v3 row_shr:4 row_mask:0xf bank_mask:0xf
	v_mov_b32_dpp v63, v7 row_shr:4 row_mask:0xf bank_mask:0xf
	v_cndmask_b32_e64 v115, v119, v5, s[10:11]
	v_cndmask_b32_e64 v114, v118, v4, s[10:11]
	v_mov_b32_dpp v120, v108 row_bcast:15 row_mask:0xa bank_mask:0xf
	s_waitcnt lgkmcnt(2)
	v_pk_mul_f32 v[60:61], v[2:3], v[60:61]
	s_waitcnt lgkmcnt(1)
	v_pk_fma_f32 v[62:63], v[2:3], v[62:63], v[6:7]
	v_cndmask_b32_e64 v3, v61, v3, s[8:9]
	v_cndmask_b32_e64 v2, v60, v2, s[8:9]
	v_cndmask_b32_e64 v7, v63, v7, s[8:9]
	v_cndmask_b32_e64 v6, v62, v6, s[8:9]
	v_mov_b32_dpp v60, v2 row_shr:8 row_mask:0xf bank_mask:0xf
	s_nop 1
	v_mov_b32_dpp v62, v6 row_shr:8 row_mask:0xf bank_mask:0xf
	v_mov_b32_dpp v61, v3 row_shr:8 row_mask:0xf bank_mask:0xf
	v_mov_b32_dpp v63, v7 row_shr:8 row_mask:0xf bank_mask:0xf
	v_mov_b32_dpp v121, v109 row_bcast:15 row_mask:0xa bank_mask:0xf
	v_mov_b32_dpp v4, v112 row_bcast:15 row_mask:0xa bank_mask:0xf
	v_mov_b32_dpp v122, v114 row_bcast:15 row_mask:0xa bank_mask:0xf
	s_waitcnt lgkmcnt(4)
	v_pk_mul_f32 v[60:61], v[2:3], v[60:61]
	s_waitcnt lgkmcnt(3)
	v_pk_fma_f32 v[62:63], v[2:3], v[62:63], v[6:7]
	v_cndmask_b32_e64 v117, v61, v3, s[10:11]
	v_cndmask_b32_e64 v116, v60, v2, s[10:11]
	v_cndmask_b32_e64 v119, v63, v7, s[10:11]
	v_cndmask_b32_e64 v118, v62, v6, s[10:11]
	v_mov_b32_dpp v5, v113 row_bcast:15 row_mask:0xa bank_mask:0xf
	v_mov_b32_dpp v123, v115 row_bcast:15 row_mask:0xa bank_mask:0xf
	v_mov_b32_dpp v6, v116 row_bcast:15 row_mask:0xa bank_mask:0xf
	v_mov_b32_dpp v124, v118 row_bcast:15 row_mask:0xa bank_mask:0xf
	v_mov_b32_dpp v7, v117 row_bcast:15 row_mask:0xa bank_mask:0xf
	v_mov_b32_dpp v125, v119 row_bcast:15 row_mask:0xa bank_mask:0xf
	s_waitcnt lgkmcnt(8)
	v_pk_fma_f32 v[2:3], v[110:111], v[120:121], v[108:109]
	s_waitcnt lgkmcnt(5)
	v_pk_mul_f32 v[60:61], v[112:113], v[4:5]
	s_waitcnt lgkmcnt(4)
	v_pk_fma_f32 v[4:5], v[112:113], v[122:123], v[114:115]
	s_waitcnt lgkmcnt(1)
	v_pk_mul_f32 v[62:63], v[116:117], v[6:7]
	s_waitcnt lgkmcnt(0)
	v_pk_fma_f32 v[6:7], v[116:117], v[124:125], v[118:119]
	v_cmp_eq_u32_e64 s[6:7], 31, v162
	v_and_b32_e32 v122, 0xffffffc0, v160
	s_and_saveexec_b64 s[2:3], s[6:7]
	s_cbranch_execz .LBB0_906
	v_or_b32_e32 v120, v164, v122
	v_lshl_add_u32 v120, v120, 2, s89
	ds_write_b128 v120, v[8:11] offset:34816
	ds_write_b128 v120, v[12:15] offset:35840
	ds_write_b128 v120, v[20:23] offset:34848
	ds_write_b128 v120, v[16:19] offset:35872
	ds_write_b128 v120, v[28:31] offset:34880
	ds_write_b128 v120, v[24:27] offset:35904
	ds_write_b128 v120, v[36:39] offset:34912
	ds_write_b128 v120, v[32:35] offset:35936
	ds_write_b128 v120, v[48:51] offset:34944
	ds_write_b128 v120, v[40:43] offset:35968
	ds_write_b128 v120, v[52:55] offset:34976
	ds_write_b128 v120, v[44:47] offset:36000
	ds_write_b128 v120, v[56:59] offset:35008
	ds_write_b128 v120, v[0:3] offset:36032
	ds_write_b128 v120, v[60:63] offset:35040
	ds_write_b128 v120, v[4:7] offset:36064
